# attention: fully resolved straight-line tail (last 4 / 3 step pairs) with folded ring addresses
# speedup vs baseline: 1.0021x; 1.0021x over previous
.Lst0_exit:
	s_cmp_lg_u32 s21, 60
	s_cbranch_scc1 .Lst0_orig
	s_cmp_lg_u32 s41, 0
	s_cbranch_scc1 .Lst0_orig
	s_and_b32 s2, s20, 0xffff
	s_cmp_lg_u32 s2, 0xc000
	s_cbranch_scc1 .Lst0_orig
	s_mov_b32 s2, s40
	s_add_i32 s2, s2, s15
	s_sub_i32 s2, s2, 64
	s_mul_hi_i32 s3, s2, 0x600
	s_mulk_i32 s2, 0x600
	s_add_u32 s2, s12, s2
	s_addc_u32 s3, s13, s3
	s_add_i32 s46, s58, 0
	s_mov_b32 m0, s46
	s_nop 0
	global_load_lds_dwordx4 v198, s[2:3]
	s_add_i32 m0, s46, 0x400
	s_nop 0
	global_load_lds_dwordx4 v194, s[2:3]
	s_mov_b32 s46, s40
	s_add_i32 s46, s46, s15
	s_addk_i32 s46, 0xff80
	s_ashr_i32 s47, s46, 31
	s_lshl_b64 s[46:47], s[46:47], 1
	s_add_u32 s46, s39, s46
	s_addc_u32 s47, s67, s47
	s_add_i32 s48, s20, 0xffffc000
	s_add_i32 s48, s58, 0x8000
	s_add_i32 m0, s48, 0xc000
	s_nop 0
	global_load_lds_dwordx4 v196, s[46:47]
	s_add_i32 m0, s48, 0xc400
	s_nop 0
	global_load_lds_dwordx4 v192, s[46:47]
	s_add_i32 s46, s20, 0xffff4000
	ds_read_b128 v[96:99], v205 offset:16384
	ds_read_b128 v[100:103], v205 offset:24576
	s_waitcnt lgkmcnt(0)
	v_mfma_f32_32x32x16_bf16 v[112:127], v[96:99], v[160:163], 0
	ds_read_b128 v[128:131], v211 offset:16384
	ds_read_b128 v[132:135], v211 offset:24576
	ds_read_b128 v[136:139], v212 offset:16384
	v_exp_f32_e32 v140, v48
	v_exp_f32_e32 v141, v49
	v_exp_f32_e32 v142, v50
	v_exp_f32_e32 v143, v51
	ds_read_b128 v[48:51], v212 offset:24576
	v_mfma_f32_32x32x16_bf16 v[96:111], v[100:103], v[160:163], 0
	v_exp_f32_e32 v144, v52
	v_exp_f32_e32 v145, v53
	v_exp_f32_e32 v146, v54
	v_exp_f32_e32 v147, v55
	s_waitcnt lgkmcnt(0)
	v_mfma_f32_32x32x16_bf16 v[112:127], v[128:131], v[164:167], v[112:127]
	ds_read_b128 v[52:55], v213 offset:16384
	v_exp_f32_e32 v148, v56
	v_exp_f32_e32 v149, v57
	v_exp_f32_e32 v150, v58
	v_exp_f32_e32 v151, v59
	v_mfma_f32_32x32x16_bf16 v[96:111], v[132:135], v[164:167], v[96:111]
	ds_read_b128 v[56:59], v213 offset:24576
	v_exp_f32_e32 v128, v60
	v_exp_f32_e32 v129, v61
	v_exp_f32_e32 v130, v62
	v_exp_f32_e32 v131, v63
	v_mfma_f32_32x32x16_bf16 v[112:127], v[136:139], v[168:171], v[112:127]
	ds_read_b128 v[60:63], v206 offset:49152
	v_exp_f32_e32 v132, v32
	v_exp_f32_e32 v133, v33
	v_exp_f32_e32 v134, v34
	v_exp_f32_e32 v135, v35
	v_mfma_f32_32x32x16_bf16 v[96:111], v[48:51], v[168:171], v[96:111]
	ds_read_b128 v[32:35], v206 offset:53248
	v_exp_f32_e32 v136, v36
	v_exp_f32_e32 v137, v37
	v_exp_f32_e32 v138, v38
	v_exp_f32_e32 v139, v39
	s_waitcnt lgkmcnt(0)
	v_mfma_f32_32x32x16_bf16 v[112:127], v[52:55], v[172:175], v[112:127]
	ds_read_b128 v[36:39], v206 offset:57344
	v_exp_f32_e32 v152, v40
	v_exp_f32_e32 v153, v41
	v_exp_f32_e32 v154, v42
	v_exp_f32_e32 v155, v43
	v_mfma_f32_32x32x16_bf16 v[96:111], v[56:59], v[172:175], v[96:111]
	ds_read_b128 v[40:43], v206 offset:61440
	v_exp_f32_e32 v156, v44
	v_exp_f32_e32 v157, v45
	v_exp_f32_e32 v158, v46
	v_exp_f32_e32 v159, v47
	v_cvt_pk_bf16_f32 v44, v140, v141
	v_cvt_pk_bf16_f32 v45, v142, v143
	v_cvt_pk_bf16_f32 v46, v144, v145
	v_cvt_pk_bf16_f32 v47, v146, v147
	s_nop 1
	v_mfma_f32_32x32x16_bf16 v[80:95], v[60:63], v[44:47], v[80:95]
	ds_read_b128 v[48:51], v207 offset:49152
	v_cvt_pk_bf16_f32 v52, v148, v149
	v_cvt_pk_bf16_f32 v53, v150, v151
	v_cvt_pk_bf16_f32 v54, v128, v129
	v_cvt_pk_bf16_f32 v55, v130, v131
	v_mfma_f32_32x32x16_bf16 v[64:79], v[32:35], v[44:47], v[64:79]
	ds_read_b128 v[56:59], v207 offset:53248
	v_pk_add_f32 v[62:63], v[146:147], v[142:143]
	v_pk_add_f32 v[60:61], v[144:145], v[140:141]
	s_waitcnt lgkmcnt(0)
	v_mfma_f32_32x32x16_bf16 v[16:31], v[36:39], v[44:47], v[16:31]
	ds_read_b128 v[32:35], v207 offset:57344
	v_add_f32_e64 v62, v150, v62
	v_add_f32_e64 v63, v151, v63
	v_add_f32_e64 v60, v148, v60
	v_add_f32_e64 v61, v149, v61
	v_pk_add_f32 v[62:63], v[130:131], v[62:63]
	v_pk_add_f32 v[60:61], v[128:129], v[60:61]
	v_mfma_f32_32x32x16_bf16 v[0:15], v[40:43], v[44:47], v[0:15]
	ds_read_b128 v[36:39], v207 offset:61440
	v_mfma_f32_32x32x16_bf16 v[80:95], v[48:51], v[52:55], v[80:95]
	ds_read_b128 v[40:43], v208 offset:49152
	v_cvt_pk_bf16_f32 v44, v132, v133
	v_cvt_pk_bf16_f32 v45, v134, v135
	v_cvt_pk_bf16_f32 v46, v136, v137
	v_cvt_pk_bf16_f32 v47, v138, v139
	v_mfma_f32_32x32x16_bf16 v[64:79], v[56:59], v[52:55], v[64:79]
	ds_read_b128 v[48:51], v208 offset:53248
	v_add_f32_e64 v62, v134, v62
	v_add_f32_e64 v63, v135, v63
	v_add_f32_e64 v60, v132, v60
	v_add_f32_e64 v61, v133, v61
	v_pk_add_f32 v[62:63], v[138:139], v[62:63]
	v_pk_add_f32 v[60:61], v[136:137], v[60:61]
	s_waitcnt lgkmcnt(0)
	v_mfma_f32_32x32x16_bf16 v[16:31], v[32:35], v[52:55], v[16:31]
	ds_read_b128 v[56:59], v208 offset:57344
	v_add_f32_e64 v62, v154, v62
	v_add_f32_e64 v63, v155, v63
	v_add_f32_e64 v60, v152, v60
	v_add_f32_e64 v61, v153, v61
	v_pk_add_f32 v[130:131], v[158:159], v[62:63]
	v_pk_add_f32 v[128:129], v[156:157], v[60:61]
	v_mfma_f32_32x32x16_bf16 v[0:15], v[36:39], v[52:55], v[0:15]
	ds_read_b128 v[32:35], v208 offset:61440
	v_mfma_f32_32x32x16_bf16 v[80:95], v[40:43], v[44:47], v[80:95]
	ds_read_b128 v[36:39], v209 offset:49152
	v_cvt_pk_bf16_f32 v52, v152, v153
	v_cvt_pk_bf16_f32 v53, v154, v155
	v_cvt_pk_bf16_f32 v54, v156, v157
	v_cvt_pk_bf16_f32 v55, v158, v159
	v_mfma_f32_32x32x16_bf16 v[64:79], v[48:51], v[44:47], v[64:79]
	ds_read_b128 v[40:43], v209 offset:53248
	s_waitcnt lgkmcnt(0)
	v_mfma_f32_32x32x16_bf16 v[16:31], v[56:59], v[44:47], v[16:31]
	ds_read_b128 v[48:51], v209 offset:57344
	v_mfma_f32_32x32x16_bf16 v[0:15], v[32:35], v[44:47], v[0:15]
	ds_read_b128 v[56:59], v209 offset:61440
	v_mfma_f32_32x32x16_bf16 v[80:95], v[36:39], v[52:55], v[80:95]
	v_mfma_f32_32x32x16_bf16 v[64:79], v[40:43], v[52:55], v[64:79]
	s_waitcnt lgkmcnt(0)
	v_mfma_f32_32x32x16_bf16 v[16:31], v[48:51], v[52:55], v[16:31]
	v_mfma_f32_32x32x16_bf16 v[0:15], v[56:59], v[52:55], v[0:15]
	s_waitcnt vmcnt(4) lgkmcnt(0)
	s_barrier
	s_mov_b32 s68, s14
	s_add_i32 s68, s68, s15
	s_mul_hi_i32 s69, s68, 0x600
	s_mulk_i32 s68, 0x600
	s_add_u32 s68, s12, s68
	s_addc_u32 s69, s13, s69
	s_add_i32 s49, 0x4000, s57
	s_mov_b32 m0, s49
	s_nop 0
	global_load_lds_dwordx4 v198, s[68:69]
	s_add_i32 m0, s49, 0x400
	s_nop 0
	global_load_lds_dwordx4 v194, s[68:69]
	s_mov_b32 s44, s40
	s_add_i32 s44, s44, s15
	s_sub_i32 s44, s44, 64
	s_ashr_i32 s45, s44, 31
	s_lshl_b64 s[44:45], s[44:45], 1
	s_add_u32 s44, s39, s44
	s_addc_u32 s45, s67, s45
	s_add_i32 s49, s58, 0xc000
	s_add_i32 m0, s49, 0xc000
	s_nop 0
	global_load_lds_dwordx4 v196, s[44:45]
	s_add_i32 m0, s49, 0xc400
	s_nop 0
	global_load_lds_dwordx4 v192, s[44:45]
	v_exp_f32_e32 v144, v112
	ds_read_b128 v[32:35], v205 offset:32768
	ds_read_b128 v[36:39], v205 offset:40960
	s_waitcnt lgkmcnt(0)
	v_mfma_f32_32x32x16_bf16 v[48:63], v[32:35], v[160:163], 0
	ds_read_b128 v[132:135], v211 offset:32768
	ds_read_b128 v[136:139], v211 offset:40960
	ds_read_b128 v[140:143], v212 offset:32768
	v_exp_f32_e32 v145, v113
	v_exp_f32_e32 v146, v114
	v_exp_f32_e32 v147, v115
	ds_read_b128 v[112:115], v212 offset:40960
	v_mfma_f32_32x32x16_bf16 v[32:47], v[36:39], v[160:163], 0
	v_exp_f32_e32 v148, v116
	v_exp_f32_e32 v149, v117
	v_exp_f32_e32 v150, v118
	v_exp_f32_e32 v151, v119
	s_waitcnt lgkmcnt(0)
	v_mfma_f32_32x32x16_bf16 v[48:63], v[132:135], v[164:167], v[48:63]
	ds_read_b128 v[116:119], v213 offset:32768
	v_exp_f32_e32 v152, v120
	v_exp_f32_e32 v153, v121
	v_exp_f32_e32 v154, v122
	v_exp_f32_e32 v155, v123
	v_mfma_f32_32x32x16_bf16 v[32:47], v[136:139], v[164:167], v[32:47]
	ds_read_b128 v[120:123], v213 offset:40960
	v_exp_f32_e32 v156, v124
	v_exp_f32_e32 v157, v125
	v_exp_f32_e32 v158, v126
	v_exp_f32_e32 v159, v127
	v_mfma_f32_32x32x16_bf16 v[48:63], v[140:143], v[168:171], v[48:63]
	ds_read_b128 v[124:127], v236
	v_exp_f32_e32 v136, v96
	v_exp_f32_e32 v137, v97
	v_exp_f32_e32 v138, v98
	v_exp_f32_e32 v139, v99
	v_mfma_f32_32x32x16_bf16 v[32:47], v[112:115], v[168:171], v[32:47]
	ds_read_b128 v[96:99], v236 offset:4096
	v_exp_f32_e32 v140, v100
	v_exp_f32_e32 v141, v101
	v_exp_f32_e32 v142, v102
	v_exp_f32_e32 v143, v103
	s_waitcnt lgkmcnt(0)
	v_mfma_f32_32x32x16_bf16 v[48:63], v[116:119], v[172:175], v[48:63]
	ds_read_b128 v[100:103], v236 offset:8192
	v_exp_f32_e32 v178, v104
	v_exp_f32_e32 v179, v105
	v_exp_f32_e32 v180, v106
	v_exp_f32_e32 v181, v107
	v_mfma_f32_32x32x16_bf16 v[32:47], v[120:123], v[172:175], v[32:47]
	ds_read_b128 v[104:107], v236 offset:12288
	v_exp_f32_e32 v182, v108
	v_exp_f32_e32 v183, v109
	v_exp_f32_e32 v184, v110
	v_exp_f32_e32 v185, v111
	v_cvt_pk_bf16_f32 v108, v144, v145
	v_cvt_pk_bf16_f32 v109, v146, v147
	v_cvt_pk_bf16_f32 v110, v148, v149
	v_cvt_pk_bf16_f32 v111, v150, v151
	s_nop 1
	v_mfma_f32_32x32x16_bf16 v[80:95], v[124:127], v[108:111], v[80:95]
	ds_read_b128 v[112:115], v237
	v_cvt_pk_bf16_f32 v116, v152, v153
	v_cvt_pk_bf16_f32 v117, v154, v155
	v_cvt_pk_bf16_f32 v118, v156, v157
	v_cvt_pk_bf16_f32 v119, v158, v159
	v_mfma_f32_32x32x16_bf16 v[64:79], v[96:99], v[108:111], v[64:79]
	ds_read_b128 v[120:123], v237 offset:4096
	v_pk_add_f32 v[126:127], v[150:151], v[146:147]
	v_pk_add_f32 v[124:125], v[148:149], v[144:145]
	s_waitcnt lgkmcnt(0)
	v_mfma_f32_32x32x16_bf16 v[16:31], v[100:103], v[108:111], v[16:31]
	ds_read_b128 v[132:135], v237 offset:8192
	v_add_f32_e64 v98, v154, v126
	v_add_f32_e64 v99, v155, v127
	v_add_f32_e64 v96, v152, v124
	v_add_f32_e64 v97, v153, v125
	v_pk_add_f32 v[98:99], v[158:159], v[98:99]
	v_pk_add_f32 v[96:97], v[156:157], v[96:97]
	v_mfma_f32_32x32x16_bf16 v[0:15], v[104:107], v[108:111], v[0:15]
	ds_read_b128 v[100:103], v237 offset:12288
	v_mfma_f32_32x32x16_bf16 v[80:95], v[112:115], v[116:119], v[80:95]
	ds_read_b128 v[104:107], v238
	v_cvt_pk_bf16_f32 v108, v136, v137
	v_cvt_pk_bf16_f32 v109, v138, v139
	v_cvt_pk_bf16_f32 v110, v140, v141
	v_cvt_pk_bf16_f32 v111, v142, v143
	v_mfma_f32_32x32x16_bf16 v[64:79], v[120:123], v[116:119], v[64:79]
	ds_read_b128 v[112:115], v238 offset:4096
	v_add_f32_e64 v98, v138, v98
	v_add_f32_e64 v99, v139, v99
	v_add_f32_e64 v96, v136, v96
	v_add_f32_e64 v97, v137, v97
	v_pk_add_f32 v[98:99], v[142:143], v[98:99]
	v_pk_add_f32 v[96:97], v[140:141], v[96:97]
	s_waitcnt lgkmcnt(0)
	v_mfma_f32_32x32x16_bf16 v[16:31], v[132:135], v[116:119], v[16:31]
	ds_read_b128 v[120:123], v238 offset:8192
	v_add_f32_e64 v98, v180, v98
	v_add_f32_e64 v99, v181, v99
	v_add_f32_e64 v96, v178, v96
	v_add_f32_e64 v97, v179, v97
	v_pk_add_f32 v[98:99], v[184:185], v[98:99]
	v_pk_add_f32 v[96:97], v[182:183], v[96:97]
	v_mfma_f32_32x32x16_bf16 v[0:15], v[100:103], v[116:119], v[0:15]
	ds_read_b128 v[124:127], v238 offset:12288
	v_mfma_f32_32x32x16_bf16 v[80:95], v[104:107], v[108:111], v[80:95]
	ds_read_b128 v[100:103], v239
	v_cvt_pk_bf16_f32 v116, v178, v179
	v_cvt_pk_bf16_f32 v117, v180, v181
	v_cvt_pk_bf16_f32 v118, v182, v183
	v_cvt_pk_bf16_f32 v119, v184, v185
	v_mfma_f32_32x32x16_bf16 v[64:79], v[112:115], v[108:111], v[64:79]
	ds_read_b128 v[104:107], v239 offset:4096
	s_waitcnt lgkmcnt(0)
	v_mfma_f32_32x32x16_bf16 v[16:31], v[120:123], v[108:111], v[16:31]
	ds_read_b128 v[112:115], v239 offset:8192
	v_mfma_f32_32x32x16_bf16 v[0:15], v[124:127], v[108:111], v[0:15]
	ds_read_b128 v[120:123], v239 offset:12288
	v_mfma_f32_32x32x16_bf16 v[80:95], v[100:103], v[116:119], v[80:95]
	v_mfma_f32_32x32x16_bf16 v[64:79], v[104:107], v[116:119], v[64:79]
	s_waitcnt lgkmcnt(0)
	v_mfma_f32_32x32x16_bf16 v[16:31], v[112:115], v[116:119], v[16:31]
	v_mfma_f32_32x32x16_bf16 v[0:15], v[120:123], v[116:119], v[0:15]
	s_waitcnt vmcnt(4) lgkmcnt(0)
	v_add_f32_e32 v100, v128, v129
	v_add_f32_e32 v101, v130, v131
	v_add_f32_e32 v100, v100, v101
	v_add_f32_e32 v96, v96, v97
	v_add_f32_e32 v97, v98, v99
	s_barrier
	v_add_f32_e32 v100, v177, v100
	v_add_f32_e32 v96, v96, v97
	v_add_f32_e32 v177, v100, v96
	s_add_i32 s21, s21, 2
	s_addk_i32 s15, 0x80
	s_add_i32 s20, s20, 0x8000
	s_mov_b32 s2, s14
	s_add_i32 s2, s2, s15
	s_sub_i32 s2, s2, 64
	s_mul_hi_i32 s3, s2, 0x600
	s_mulk_i32 s2, 0x600
	s_add_u32 s2, s12, s2
	s_addc_u32 s3, s13, s3
	s_add_i32 s46, s58, 0x8000
	s_mov_b32 m0, s46
	s_nop 0
	global_load_lds_dwordx4 v198, s[2:3]
	s_add_i32 m0, s46, 0x400
	s_nop 0
	global_load_lds_dwordx4 v194, s[2:3]
	s_mov_b32 s46, s14
	s_add_i32 s46, s46, s15
	s_addk_i32 s46, 0xff80
	s_ashr_i32 s47, s46, 31
	s_lshl_b64 s[46:47], s[46:47], 1
	s_add_u32 s46, s39, s46
	s_addc_u32 s47, s67, s47
	s_add_i32 s48, s20, 0xffffc000
	s_add_i32 s48, s58, 0
	s_add_i32 m0, s48, 0xc000
	s_nop 0
	global_load_lds_dwordx4 v196, s[46:47]
	s_add_i32 m0, s48, 0xc400
	s_nop 0
	global_load_lds_dwordx4 v192, s[46:47]
	s_add_i32 s46, s20, 0xffff4000
	ds_read_b128 v[96:99], v205
	ds_read_b128 v[100:103], v205 offset:8192
	s_waitcnt lgkmcnt(0)
	v_mfma_f32_32x32x16_bf16 v[112:127], v[96:99], v[160:163], 0
	ds_read_b128 v[128:131], v211
	ds_read_b128 v[132:135], v211 offset:8192
	ds_read_b128 v[136:139], v212
	v_exp_f32_e32 v140, v48
	v_exp_f32_e32 v141, v49
	v_exp_f32_e32 v142, v50
	v_exp_f32_e32 v143, v51
	ds_read_b128 v[48:51], v212 offset:8192
	v_mfma_f32_32x32x16_bf16 v[96:111], v[100:103], v[160:163], 0
	v_exp_f32_e32 v144, v52
	v_exp_f32_e32 v145, v53
	v_exp_f32_e32 v146, v54
	v_exp_f32_e32 v147, v55
	s_waitcnt lgkmcnt(0)
	v_mfma_f32_32x32x16_bf16 v[112:127], v[128:131], v[164:167], v[112:127]
	ds_read_b128 v[52:55], v213
	v_exp_f32_e32 v148, v56
	v_exp_f32_e32 v149, v57
	v_exp_f32_e32 v150, v58
	v_exp_f32_e32 v151, v59
	v_mfma_f32_32x32x16_bf16 v[96:111], v[132:135], v[164:167], v[96:111]
	ds_read_b128 v[56:59], v213 offset:8192
	v_exp_f32_e32 v128, v60
	v_exp_f32_e32 v129, v61
	v_exp_f32_e32 v130, v62
	v_exp_f32_e32 v131, v63
	v_mfma_f32_32x32x16_bf16 v[112:127], v[136:139], v[168:171], v[112:127]
	ds_read_b128 v[60:63], v236 offset:16384
	v_exp_f32_e32 v132, v32
	v_exp_f32_e32 v133, v33
	v_exp_f32_e32 v134, v34
	v_exp_f32_e32 v135, v35
	v_mfma_f32_32x32x16_bf16 v[96:111], v[48:51], v[168:171], v[96:111]
	ds_read_b128 v[32:35], v236 offset:20480
	v_exp_f32_e32 v136, v36
	v_exp_f32_e32 v137, v37
	v_exp_f32_e32 v138, v38
	v_exp_f32_e32 v139, v39
	s_waitcnt lgkmcnt(0)
	v_mfma_f32_32x32x16_bf16 v[112:127], v[52:55], v[172:175], v[112:127]
	ds_read_b128 v[36:39], v236 offset:24576
	v_exp_f32_e32 v152, v40
	v_exp_f32_e32 v153, v41
	v_exp_f32_e32 v154, v42
	v_exp_f32_e32 v155, v43
	v_mfma_f32_32x32x16_bf16 v[96:111], v[56:59], v[172:175], v[96:111]
	ds_read_b128 v[40:43], v236 offset:28672
	v_exp_f32_e32 v156, v44
	v_exp_f32_e32 v157, v45
	v_exp_f32_e32 v158, v46
	v_exp_f32_e32 v159, v47
	v_cvt_pk_bf16_f32 v44, v140, v141
	v_cvt_pk_bf16_f32 v45, v142, v143
	v_cvt_pk_bf16_f32 v46, v144, v145
	v_cvt_pk_bf16_f32 v47, v146, v147
	s_nop 1
	v_mfma_f32_32x32x16_bf16 v[80:95], v[60:63], v[44:47], v[80:95]
	ds_read_b128 v[48:51], v237 offset:16384
	v_cvt_pk_bf16_f32 v52, v148, v149
	v_cvt_pk_bf16_f32 v53, v150, v151
	v_cvt_pk_bf16_f32 v54, v128, v129
	v_cvt_pk_bf16_f32 v55, v130, v131
	v_mfma_f32_32x32x16_bf16 v[64:79], v[32:35], v[44:47], v[64:79]
	ds_read_b128 v[56:59], v237 offset:20480
	v_pk_add_f32 v[62:63], v[146:147], v[142:143]
	v_pk_add_f32 v[60:61], v[144:145], v[140:141]
	s_waitcnt lgkmcnt(0)
	v_mfma_f32_32x32x16_bf16 v[16:31], v[36:39], v[44:47], v[16:31]
	ds_read_b128 v[32:35], v237 offset:24576
	v_add_f32_e64 v62, v150, v62
	v_add_f32_e64 v63, v151, v63
	v_add_f32_e64 v60, v148, v60
	v_add_f32_e64 v61, v149, v61
	v_pk_add_f32 v[62:63], v[130:131], v[62:63]
	v_pk_add_f32 v[60:61], v[128:129], v[60:61]
	v_mfma_f32_32x32x16_bf16 v[0:15], v[40:43], v[44:47], v[0:15]
	ds_read_b128 v[36:39], v237 offset:28672
	v_mfma_f32_32x32x16_bf16 v[80:95], v[48:51], v[52:55], v[80:95]
	ds_read_b128 v[40:43], v238 offset:16384
	v_cvt_pk_bf16_f32 v44, v132, v133
	v_cvt_pk_bf16_f32 v45, v134, v135
	v_cvt_pk_bf16_f32 v46, v136, v137
	v_cvt_pk_bf16_f32 v47, v138, v139
	v_mfma_f32_32x32x16_bf16 v[64:79], v[56:59], v[52:55], v[64:79]
	ds_read_b128 v[48:51], v238 offset:20480
	v_add_f32_e64 v62, v134, v62
	v_add_f32_e64 v63, v135, v63
	v_add_f32_e64 v60, v132, v60
	v_add_f32_e64 v61, v133, v61
	v_pk_add_f32 v[62:63], v[138:139], v[62:63]
	v_pk_add_f32 v[60:61], v[136:137], v[60:61]
	s_waitcnt lgkmcnt(0)
	v_mfma_f32_32x32x16_bf16 v[16:31], v[32:35], v[52:55], v[16:31]
	ds_read_b128 v[56:59], v238 offset:24576
	v_add_f32_e64 v62, v154, v62
	v_add_f32_e64 v63, v155, v63
	v_add_f32_e64 v60, v152, v60
	v_add_f32_e64 v61, v153, v61
	v_pk_add_f32 v[130:131], v[158:159], v[62:63]
	v_pk_add_f32 v[128:129], v[156:157], v[60:61]
	v_mfma_f32_32x32x16_bf16 v[0:15], v[36:39], v[52:55], v[0:15]
	ds_read_b128 v[32:35], v238 offset:28672
	v_mfma_f32_32x32x16_bf16 v[80:95], v[40:43], v[44:47], v[80:95]
	ds_read_b128 v[36:39], v239 offset:16384
	v_cvt_pk_bf16_f32 v52, v152, v153
	v_cvt_pk_bf16_f32 v53, v154, v155
	v_cvt_pk_bf16_f32 v54, v156, v157
	v_cvt_pk_bf16_f32 v55, v158, v159
	v_mfma_f32_32x32x16_bf16 v[64:79], v[48:51], v[44:47], v[64:79]
	ds_read_b128 v[40:43], v239 offset:20480
	s_waitcnt lgkmcnt(0)
	v_mfma_f32_32x32x16_bf16 v[16:31], v[56:59], v[44:47], v[16:31]
	ds_read_b128 v[48:51], v239 offset:24576
	v_mfma_f32_32x32x16_bf16 v[0:15], v[32:35], v[44:47], v[0:15]
	ds_read_b128 v[56:59], v239 offset:28672
	v_mfma_f32_32x32x16_bf16 v[80:95], v[36:39], v[52:55], v[80:95]
	v_mfma_f32_32x32x16_bf16 v[64:79], v[40:43], v[52:55], v[64:79]
	s_waitcnt lgkmcnt(0)
	v_mfma_f32_32x32x16_bf16 v[16:31], v[48:51], v[52:55], v[16:31]
	v_mfma_f32_32x32x16_bf16 v[0:15], v[56:59], v[52:55], v[0:15]
	s_waitcnt vmcnt(4) lgkmcnt(0)
	s_barrier
	s_mov_b32 s68, s14
	s_add_i32 s68, s68, s15
	s_mul_hi_i32 s69, s68, 0x600
	s_mulk_i32 s68, 0x600
	s_add_u32 s68, s12, s68
	s_addc_u32 s69, s13, s69
	s_add_i32 s49, 0, s57
	s_mov_b32 m0, s49
	s_nop 0
	global_load_lds_dwordx4 v198, s[68:69]
	s_add_i32 m0, s49, 0x400
	s_nop 0
	global_load_lds_dwordx4 v194, s[68:69]
	s_mov_b32 s44, s14
	s_add_i32 s44, s44, s15
	s_sub_i32 s44, s44, 64
	s_ashr_i32 s45, s44, 31
	s_lshl_b64 s[44:45], s[44:45], 1
	s_add_u32 s44, s39, s44
	s_addc_u32 s45, s67, s45
	s_add_i32 s49, s58, 0x4000
	s_add_i32 m0, s49, 0xc000
	s_nop 0
	global_load_lds_dwordx4 v196, s[44:45]
	s_add_i32 m0, s49, 0xc400
	s_nop 0
	global_load_lds_dwordx4 v192, s[44:45]
	v_exp_f32_e32 v144, v112
	ds_read_b128 v[32:35], v205 offset:16384
	ds_read_b128 v[36:39], v205 offset:24576
	s_waitcnt lgkmcnt(0)
	v_mfma_f32_32x32x16_bf16 v[48:63], v[32:35], v[160:163], 0
	ds_read_b128 v[132:135], v211 offset:16384
	ds_read_b128 v[136:139], v211 offset:24576
	ds_read_b128 v[140:143], v212 offset:16384
	v_exp_f32_e32 v145, v113
	v_exp_f32_e32 v146, v114
	v_exp_f32_e32 v147, v115
	ds_read_b128 v[112:115], v212 offset:24576
	v_mfma_f32_32x32x16_bf16 v[32:47], v[36:39], v[160:163], 0
	v_exp_f32_e32 v148, v116
	v_exp_f32_e32 v149, v117
	v_exp_f32_e32 v150, v118
	v_exp_f32_e32 v151, v119
	s_waitcnt lgkmcnt(0)
	v_mfma_f32_32x32x16_bf16 v[48:63], v[132:135], v[164:167], v[48:63]
	ds_read_b128 v[116:119], v213 offset:16384
	v_exp_f32_e32 v152, v120
	v_exp_f32_e32 v153, v121
	v_exp_f32_e32 v154, v122
	v_exp_f32_e32 v155, v123
	v_mfma_f32_32x32x16_bf16 v[32:47], v[136:139], v[164:167], v[32:47]
	ds_read_b128 v[120:123], v213 offset:24576
	v_exp_f32_e32 v156, v124
	v_exp_f32_e32 v157, v125
	v_exp_f32_e32 v158, v126
	v_exp_f32_e32 v159, v127
	v_mfma_f32_32x32x16_bf16 v[48:63], v[140:143], v[168:171], v[48:63]
	ds_read_b128 v[124:127], v236 offset:32768
	v_exp_f32_e32 v136, v96
	v_exp_f32_e32 v137, v97
	v_exp_f32_e32 v138, v98
	v_exp_f32_e32 v139, v99
	v_mfma_f32_32x32x16_bf16 v[32:47], v[112:115], v[168:171], v[32:47]
	ds_read_b128 v[96:99], v236 offset:36864
	v_exp_f32_e32 v140, v100
	v_exp_f32_e32 v141, v101
	v_exp_f32_e32 v142, v102
	v_exp_f32_e32 v143, v103
	s_waitcnt lgkmcnt(0)
	v_mfma_f32_32x32x16_bf16 v[48:63], v[116:119], v[172:175], v[48:63]
	ds_read_b128 v[100:103], v236 offset:40960
	v_exp_f32_e32 v178, v104
	v_exp_f32_e32 v179, v105
	v_exp_f32_e32 v180, v106
	v_exp_f32_e32 v181, v107
	v_mfma_f32_32x32x16_bf16 v[32:47], v[120:123], v[172:175], v[32:47]
	ds_read_b128 v[104:107], v236 offset:45056
	v_exp_f32_e32 v182, v108
	v_exp_f32_e32 v183, v109
	v_exp_f32_e32 v184, v110
	v_exp_f32_e32 v185, v111
	v_cvt_pk_bf16_f32 v108, v144, v145
	v_cvt_pk_bf16_f32 v109, v146, v147
	v_cvt_pk_bf16_f32 v110, v148, v149
	v_cvt_pk_bf16_f32 v111, v150, v151
	s_nop 1
	v_mfma_f32_32x32x16_bf16 v[80:95], v[124:127], v[108:111], v[80:95]
	ds_read_b128 v[112:115], v237 offset:32768
	v_cvt_pk_bf16_f32 v116, v152, v153
	v_cvt_pk_bf16_f32 v117, v154, v155
	v_cvt_pk_bf16_f32 v118, v156, v157
	v_cvt_pk_bf16_f32 v119, v158, v159
	v_mfma_f32_32x32x16_bf16 v[64:79], v[96:99], v[108:111], v[64:79]
	ds_read_b128 v[120:123], v237 offset:36864
	v_pk_add_f32 v[126:127], v[150:151], v[146:147]
	v_pk_add_f32 v[124:125], v[148:149], v[144:145]
	s_waitcnt lgkmcnt(0)
	v_mfma_f32_32x32x16_bf16 v[16:31], v[100:103], v[108:111], v[16:31]
	ds_read_b128 v[132:135], v237 offset:40960
	v_add_f32_e64 v98, v154, v126
	v_add_f32_e64 v99, v155, v127
	v_add_f32_e64 v96, v152, v124
	v_add_f32_e64 v97, v153, v125
	v_pk_add_f32 v[98:99], v[158:159], v[98:99]
	v_pk_add_f32 v[96:97], v[156:157], v[96:97]
	v_mfma_f32_32x32x16_bf16 v[0:15], v[104:107], v[108:111], v[0:15]
	ds_read_b128 v[100:103], v237 offset:45056
	v_mfma_f32_32x32x16_bf16 v[80:95], v[112:115], v[116:119], v[80:95]
	ds_read_b128 v[104:107], v238 offset:32768
	v_cvt_pk_bf16_f32 v108, v136, v137
	v_cvt_pk_bf16_f32 v109, v138, v139
	v_cvt_pk_bf16_f32 v110, v140, v141
	v_cvt_pk_bf16_f32 v111, v142, v143
	v_mfma_f32_32x32x16_bf16 v[64:79], v[120:123], v[116:119], v[64:79]
	ds_read_b128 v[112:115], v238 offset:36864
	v_add_f32_e64 v98, v138, v98
	v_add_f32_e64 v99, v139, v99
	v_add_f32_e64 v96, v136, v96
	v_add_f32_e64 v97, v137, v97
	v_pk_add_f32 v[98:99], v[142:143], v[98:99]
	v_pk_add_f32 v[96:97], v[140:141], v[96:97]
	s_waitcnt lgkmcnt(0)
	v_mfma_f32_32x32x16_bf16 v[16:31], v[132:135], v[116:119], v[16:31]
	ds_read_b128 v[120:123], v238 offset:40960
	v_add_f32_e64 v98, v180, v98
	v_add_f32_e64 v99, v181, v99
	v_add_f32_e64 v96, v178, v96
	v_add_f32_e64 v97, v179, v97
	v_pk_add_f32 v[98:99], v[184:185], v[98:99]
	v_pk_add_f32 v[96:97], v[182:183], v[96:97]
	v_mfma_f32_32x32x16_bf16 v[0:15], v[100:103], v[116:119], v[0:15]
	ds_read_b128 v[124:127], v238 offset:45056
	v_mfma_f32_32x32x16_bf16 v[80:95], v[104:107], v[108:111], v[80:95]
	ds_read_b128 v[100:103], v239 offset:32768
	v_cvt_pk_bf16_f32 v116, v178, v179
	v_cvt_pk_bf16_f32 v117, v180, v181
	v_cvt_pk_bf16_f32 v118, v182, v183
	v_cvt_pk_bf16_f32 v119, v184, v185
	v_mfma_f32_32x32x16_bf16 v[64:79], v[112:115], v[108:111], v[64:79]
	ds_read_b128 v[104:107], v239 offset:36864
	s_waitcnt lgkmcnt(0)
	v_mfma_f32_32x32x16_bf16 v[16:31], v[120:123], v[108:111], v[16:31]
	ds_read_b128 v[112:115], v239 offset:40960
	v_mfma_f32_32x32x16_bf16 v[0:15], v[124:127], v[108:111], v[0:15]
	ds_read_b128 v[120:123], v239 offset:45056
	v_mfma_f32_32x32x16_bf16 v[80:95], v[100:103], v[116:119], v[80:95]
	v_mfma_f32_32x32x16_bf16 v[64:79], v[104:107], v[116:119], v[64:79]
	s_waitcnt lgkmcnt(0)
	v_mfma_f32_32x32x16_bf16 v[16:31], v[112:115], v[116:119], v[16:31]
	v_mfma_f32_32x32x16_bf16 v[0:15], v[120:123], v[116:119], v[0:15]
	s_waitcnt vmcnt(4) lgkmcnt(0)
	v_add_f32_e32 v100, v128, v129
	v_add_f32_e32 v101, v130, v131
	v_add_f32_e32 v100, v100, v101
	v_add_f32_e32 v96, v96, v97
	v_add_f32_e32 v97, v98, v99
	s_barrier
	v_add_f32_e32 v100, v177, v100
	v_add_f32_e32 v96, v96, v97
	v_add_f32_e32 v177, v100, v96
	s_add_i32 s21, s21, 2
	s_addk_i32 s15, 0x80
	s_add_i32 s20, s20, 0x8000
	s_mov_b32 s2, s14
	s_add_i32 s2, s2, s15
	s_sub_i32 s2, s2, 64
	s_mul_hi_i32 s3, s2, 0x600
	s_mulk_i32 s2, 0x600
	s_add_u32 s2, s12, s2
	s_addc_u32 s3, s13, s3
	s_add_i32 s46, s58, 0x4000
	s_mov_b32 m0, s46
	s_nop 0
	global_load_lds_dwordx4 v198, s[2:3]
	s_add_i32 m0, s46, 0x400
	s_nop 0
	global_load_lds_dwordx4 v194, s[2:3]
	s_mov_b32 s46, s14
	s_add_i32 s46, s46, s15
	s_addk_i32 s46, 0xff80
	s_ashr_i32 s47, s46, 31
	s_lshl_b64 s[46:47], s[46:47], 1
	s_add_u32 s46, s39, s46
	s_addc_u32 s47, s67, s47
	s_add_i32 s48, s20, 0xffffc000
	s_add_i32 s48, s58, 0x8000
	s_add_i32 m0, s48, 0xc000
	s_nop 0
	global_load_lds_dwordx4 v196, s[46:47]
	s_add_i32 m0, s48, 0xc400
	s_nop 0
	global_load_lds_dwordx4 v192, s[46:47]
	s_add_i32 s46, s20, 0xffff4000
	ds_read_b128 v[96:99], v205 offset:32768
	ds_read_b128 v[100:103], v205 offset:40960
	s_waitcnt lgkmcnt(0)
	v_mfma_f32_32x32x16_bf16 v[112:127], v[96:99], v[160:163], 0
	ds_read_b128 v[128:131], v211 offset:32768
	ds_read_b128 v[132:135], v211 offset:40960
	ds_read_b128 v[136:139], v212 offset:32768
	v_exp_f32_e32 v140, v48
	v_exp_f32_e32 v141, v49
	v_exp_f32_e32 v142, v50
	v_exp_f32_e32 v143, v51
	ds_read_b128 v[48:51], v212 offset:40960
	v_mfma_f32_32x32x16_bf16 v[96:111], v[100:103], v[160:163], 0
	v_exp_f32_e32 v144, v52
	v_exp_f32_e32 v145, v53
	v_exp_f32_e32 v146, v54
	v_exp_f32_e32 v147, v55
	s_waitcnt lgkmcnt(0)
	v_mfma_f32_32x32x16_bf16 v[112:127], v[128:131], v[164:167], v[112:127]
	ds_read_b128 v[52:55], v213 offset:32768
	v_exp_f32_e32 v148, v56
	v_exp_f32_e32 v149, v57
	v_exp_f32_e32 v150, v58
	v_exp_f32_e32 v151, v59
	v_mfma_f32_32x32x16_bf16 v[96:111], v[132:135], v[164:167], v[96:111]
	ds_read_b128 v[56:59], v213 offset:40960
	v_exp_f32_e32 v128, v60
	v_exp_f32_e32 v129, v61
	v_exp_f32_e32 v130, v62
	v_exp_f32_e32 v131, v63
	v_mfma_f32_32x32x16_bf16 v[112:127], v[136:139], v[168:171], v[112:127]
	ds_read_b128 v[60:63], v206 offset:49152
	v_exp_f32_e32 v132, v32
	v_exp_f32_e32 v133, v33
	v_exp_f32_e32 v134, v34
	v_exp_f32_e32 v135, v35
	v_mfma_f32_32x32x16_bf16 v[96:111], v[48:51], v[168:171], v[96:111]
	ds_read_b128 v[32:35], v206 offset:53248
	v_exp_f32_e32 v136, v36
	v_exp_f32_e32 v137, v37
	v_exp_f32_e32 v138, v38
	v_exp_f32_e32 v139, v39
	s_waitcnt lgkmcnt(0)
	v_mfma_f32_32x32x16_bf16 v[112:127], v[52:55], v[172:175], v[112:127]
	ds_read_b128 v[36:39], v206 offset:57344
	v_exp_f32_e32 v152, v40
	v_exp_f32_e32 v153, v41
	v_exp_f32_e32 v154, v42
	v_exp_f32_e32 v155, v43
	v_mfma_f32_32x32x16_bf16 v[96:111], v[56:59], v[172:175], v[96:111]
	ds_read_b128 v[40:43], v206 offset:61440
	v_exp_f32_e32 v156, v44
	v_exp_f32_e32 v157, v45
	v_exp_f32_e32 v158, v46
	v_exp_f32_e32 v159, v47
	v_cvt_pk_bf16_f32 v44, v140, v141
	v_cvt_pk_bf16_f32 v45, v142, v143
	v_cvt_pk_bf16_f32 v46, v144, v145
	v_cvt_pk_bf16_f32 v47, v146, v147
	s_nop 1
	v_mfma_f32_32x32x16_bf16 v[80:95], v[60:63], v[44:47], v[80:95]
	ds_read_b128 v[48:51], v207 offset:49152
	v_cvt_pk_bf16_f32 v52, v148, v149
	v_cvt_pk_bf16_f32 v53, v150, v151
	v_cvt_pk_bf16_f32 v54, v128, v129
	v_cvt_pk_bf16_f32 v55, v130, v131
	v_mfma_f32_32x32x16_bf16 v[64:79], v[32:35], v[44:47], v[64:79]
	ds_read_b128 v[56:59], v207 offset:53248
	v_pk_add_f32 v[62:63], v[146:147], v[142:143]
	v_pk_add_f32 v[60:61], v[144:145], v[140:141]
	s_waitcnt lgkmcnt(0)
	v_mfma_f32_32x32x16_bf16 v[16:31], v[36:39], v[44:47], v[16:31]
	ds_read_b128 v[32:35], v207 offset:57344
	v_add_f32_e64 v62, v150, v62
	v_add_f32_e64 v63, v151, v63
	v_add_f32_e64 v60, v148, v60
	v_add_f32_e64 v61, v149, v61
	v_pk_add_f32 v[62:63], v[130:131], v[62:63]
	v_pk_add_f32 v[60:61], v[128:129], v[60:61]
	v_mfma_f32_32x32x16_bf16 v[0:15], v[40:43], v[44:47], v[0:15]
	ds_read_b128 v[36:39], v207 offset:61440
	v_mfma_f32_32x32x16_bf16 v[80:95], v[48:51], v[52:55], v[80:95]
	ds_read_b128 v[40:43], v208 offset:49152
	v_cvt_pk_bf16_f32 v44, v132, v133
	v_cvt_pk_bf16_f32 v45, v134, v135
	v_cvt_pk_bf16_f32 v46, v136, v137
	v_cvt_pk_bf16_f32 v47, v138, v139
	v_mfma_f32_32x32x16_bf16 v[64:79], v[56:59], v[52:55], v[64:79]
	ds_read_b128 v[48:51], v208 offset:53248
	v_add_f32_e64 v62, v134, v62
	v_add_f32_e64 v63, v135, v63
	v_add_f32_e64 v60, v132, v60
	v_add_f32_e64 v61, v133, v61
	v_pk_add_f32 v[62:63], v[138:139], v[62:63]
	v_pk_add_f32 v[60:61], v[136:137], v[60:61]
	s_waitcnt lgkmcnt(0)
	v_mfma_f32_32x32x16_bf16 v[16:31], v[32:35], v[52:55], v[16:31]
	ds_read_b128 v[56:59], v208 offset:57344
	v_add_f32_e64 v62, v154, v62
	v_add_f32_e64 v63, v155, v63
	v_add_f32_e64 v60, v152, v60
	v_add_f32_e64 v61, v153, v61
	v_pk_add_f32 v[130:131], v[158:159], v[62:63]
	v_pk_add_f32 v[128:129], v[156:157], v[60:61]
	v_mfma_f32_32x32x16_bf16 v[0:15], v[36:39], v[52:55], v[0:15]
	ds_read_b128 v[32:35], v208 offset:61440
	v_mfma_f32_32x32x16_bf16 v[80:95], v[40:43], v[44:47], v[80:95]
	ds_read_b128 v[36:39], v209 offset:49152
	v_cvt_pk_bf16_f32 v52, v152, v153
	v_cvt_pk_bf16_f32 v53, v154, v155
	v_cvt_pk_bf16_f32 v54, v156, v157
	v_cvt_pk_bf16_f32 v55, v158, v159
	v_mfma_f32_32x32x16_bf16 v[64:79], v[48:51], v[44:47], v[64:79]
	ds_read_b128 v[40:43], v209 offset:53248
	s_waitcnt lgkmcnt(0)
	v_mfma_f32_32x32x16_bf16 v[16:31], v[56:59], v[44:47], v[16:31]
	ds_read_b128 v[48:51], v209 offset:57344
	v_mfma_f32_32x32x16_bf16 v[0:15], v[32:35], v[44:47], v[0:15]
	ds_read_b128 v[56:59], v209 offset:61440
	v_mfma_f32_32x32x16_bf16 v[80:95], v[36:39], v[52:55], v[80:95]
	v_mfma_f32_32x32x16_bf16 v[64:79], v[40:43], v[52:55], v[64:79]
	s_waitcnt lgkmcnt(0)
	v_mfma_f32_32x32x16_bf16 v[16:31], v[48:51], v[52:55], v[16:31]
	v_mfma_f32_32x32x16_bf16 v[0:15], v[56:59], v[52:55], v[0:15]
	s_waitcnt vmcnt(4) lgkmcnt(0)
	s_barrier
	s_mov_b32 s44, s14
	s_add_i32 s44, s44, s15
	s_sub_i32 s44, s44, 64
	s_ashr_i32 s45, s44, 31
	s_lshl_b64 s[44:45], s[44:45], 1
	s_add_u32 s44, s39, s44
	s_addc_u32 s45, s67, s45
	s_add_i32 s49, s58, 0xc000
	s_add_i32 m0, s49, 0xc000
	s_nop 0
	global_load_lds_dwordx4 v196, s[44:45]
	s_add_i32 m0, s49, 0xc400
	s_nop 0
	global_load_lds_dwordx4 v192, s[44:45]
	v_exp_f32_e32 v144, v112
	ds_read_b128 v[32:35], v205
	ds_read_b128 v[36:39], v205 offset:8192
	s_waitcnt lgkmcnt(0)
	v_mfma_f32_32x32x16_bf16 v[48:63], v[32:35], v[160:163], 0
	ds_read_b128 v[132:135], v211
	ds_read_b128 v[136:139], v211 offset:8192
	ds_read_b128 v[140:143], v212
	v_exp_f32_e32 v145, v113
	v_exp_f32_e32 v146, v114
	v_exp_f32_e32 v147, v115
	ds_read_b128 v[112:115], v212 offset:8192
	v_mfma_f32_32x32x16_bf16 v[32:47], v[36:39], v[160:163], 0
	v_exp_f32_e32 v148, v116
	v_exp_f32_e32 v149, v117
	v_exp_f32_e32 v150, v118
	v_exp_f32_e32 v151, v119
	s_waitcnt lgkmcnt(0)
	v_mfma_f32_32x32x16_bf16 v[48:63], v[132:135], v[164:167], v[48:63]
	ds_read_b128 v[116:119], v213
	v_exp_f32_e32 v152, v120
	v_exp_f32_e32 v153, v121
	v_exp_f32_e32 v154, v122
	v_exp_f32_e32 v155, v123
	v_mfma_f32_32x32x16_bf16 v[32:47], v[136:139], v[164:167], v[32:47]
	ds_read_b128 v[120:123], v213 offset:8192
	v_exp_f32_e32 v156, v124
	v_exp_f32_e32 v157, v125
	v_exp_f32_e32 v158, v126
	v_exp_f32_e32 v159, v127
	v_mfma_f32_32x32x16_bf16 v[48:63], v[140:143], v[168:171], v[48:63]
	ds_read_b128 v[124:127], v236
	v_exp_f32_e32 v136, v96
	v_exp_f32_e32 v137, v97
	v_exp_f32_e32 v138, v98
	v_exp_f32_e32 v139, v99
	v_mfma_f32_32x32x16_bf16 v[32:47], v[112:115], v[168:171], v[32:47]
	ds_read_b128 v[96:99], v236 offset:4096
	v_exp_f32_e32 v140, v100
	v_exp_f32_e32 v141, v101
	v_exp_f32_e32 v142, v102
	v_exp_f32_e32 v143, v103
	s_waitcnt lgkmcnt(0)
	v_mfma_f32_32x32x16_bf16 v[48:63], v[116:119], v[172:175], v[48:63]
	ds_read_b128 v[100:103], v236 offset:8192
	v_exp_f32_e32 v178, v104
	v_exp_f32_e32 v179, v105
	v_exp_f32_e32 v180, v106
	v_exp_f32_e32 v181, v107
	v_mfma_f32_32x32x16_bf16 v[32:47], v[120:123], v[172:175], v[32:47]
	ds_read_b128 v[104:107], v236 offset:12288
	v_exp_f32_e32 v182, v108
	v_exp_f32_e32 v183, v109
	v_exp_f32_e32 v184, v110
	v_exp_f32_e32 v185, v111
	v_cvt_pk_bf16_f32 v108, v144, v145
	v_cvt_pk_bf16_f32 v109, v146, v147
	v_cvt_pk_bf16_f32 v110, v148, v149
	v_cvt_pk_bf16_f32 v111, v150, v151
	s_nop 1
	v_mfma_f32_32x32x16_bf16 v[80:95], v[124:127], v[108:111], v[80:95]
	ds_read_b128 v[112:115], v237
	v_cvt_pk_bf16_f32 v116, v152, v153
	v_cvt_pk_bf16_f32 v117, v154, v155
	v_cvt_pk_bf16_f32 v118, v156, v157
	v_cvt_pk_bf16_f32 v119, v158, v159
	v_mfma_f32_32x32x16_bf16 v[64:79], v[96:99], v[108:111], v[64:79]
	ds_read_b128 v[120:123], v237 offset:4096
	v_pk_add_f32 v[126:127], v[150:151], v[146:147]
	v_pk_add_f32 v[124:125], v[148:149], v[144:145]
	s_waitcnt lgkmcnt(0)
	v_mfma_f32_32x32x16_bf16 v[16:31], v[100:103], v[108:111], v[16:31]
	ds_read_b128 v[132:135], v237 offset:8192
	v_add_f32_e64 v98, v154, v126
	v_add_f32_e64 v99, v155, v127
	v_add_f32_e64 v96, v152, v124
	v_add_f32_e64 v97, v153, v125
	v_pk_add_f32 v[98:99], v[158:159], v[98:99]
	v_pk_add_f32 v[96:97], v[156:157], v[96:97]
	v_mfma_f32_32x32x16_bf16 v[0:15], v[104:107], v[108:111], v[0:15]
	ds_read_b128 v[100:103], v237 offset:12288
	v_mfma_f32_32x32x16_bf16 v[80:95], v[112:115], v[116:119], v[80:95]
	ds_read_b128 v[104:107], v238
	v_cvt_pk_bf16_f32 v108, v136, v137
	v_cvt_pk_bf16_f32 v109, v138, v139
	v_cvt_pk_bf16_f32 v110, v140, v141
	v_cvt_pk_bf16_f32 v111, v142, v143
	v_mfma_f32_32x32x16_bf16 v[64:79], v[120:123], v[116:119], v[64:79]
	ds_read_b128 v[112:115], v238 offset:4096
	v_add_f32_e64 v98, v138, v98
	v_add_f32_e64 v99, v139, v99
	v_add_f32_e64 v96, v136, v96
	v_add_f32_e64 v97, v137, v97
	v_pk_add_f32 v[98:99], v[142:143], v[98:99]
	v_pk_add_f32 v[96:97], v[140:141], v[96:97]
	s_waitcnt lgkmcnt(0)
	v_mfma_f32_32x32x16_bf16 v[16:31], v[132:135], v[116:119], v[16:31]
	ds_read_b128 v[120:123], v238 offset:8192
	v_add_f32_e64 v98, v180, v98
	v_add_f32_e64 v99, v181, v99
	v_add_f32_e64 v96, v178, v96
	v_add_f32_e64 v97, v179, v97
	v_pk_add_f32 v[98:99], v[184:185], v[98:99]
	v_pk_add_f32 v[96:97], v[182:183], v[96:97]
	v_mfma_f32_32x32x16_bf16 v[0:15], v[100:103], v[116:119], v[0:15]
	ds_read_b128 v[124:127], v238 offset:12288
	v_mfma_f32_32x32x16_bf16 v[80:95], v[104:107], v[108:111], v[80:95]
	ds_read_b128 v[100:103], v239
	v_cvt_pk_bf16_f32 v116, v178, v179
	v_cvt_pk_bf16_f32 v117, v180, v181
	v_cvt_pk_bf16_f32 v118, v182, v183
	v_cvt_pk_bf16_f32 v119, v184, v185
	v_mfma_f32_32x32x16_bf16 v[64:79], v[112:115], v[108:111], v[64:79]
	ds_read_b128 v[104:107], v239 offset:4096
	s_waitcnt lgkmcnt(0)
	v_mfma_f32_32x32x16_bf16 v[16:31], v[120:123], v[108:111], v[16:31]
	ds_read_b128 v[112:115], v239 offset:8192
	v_mfma_f32_32x32x16_bf16 v[0:15], v[124:127], v[108:111], v[0:15]
	ds_read_b128 v[120:123], v239 offset:12288
	v_mfma_f32_32x32x16_bf16 v[80:95], v[100:103], v[116:119], v[80:95]
	v_mfma_f32_32x32x16_bf16 v[64:79], v[104:107], v[116:119], v[64:79]
	s_waitcnt lgkmcnt(0)
	v_mfma_f32_32x32x16_bf16 v[16:31], v[112:115], v[116:119], v[16:31]
	v_mfma_f32_32x32x16_bf16 v[0:15], v[120:123], v[116:119], v[0:15]
	s_waitcnt vmcnt(2) lgkmcnt(0)
	v_add_f32_e32 v100, v128, v129
	v_add_f32_e32 v101, v130, v131
	v_add_f32_e32 v100, v100, v101
	v_add_f32_e32 v96, v96, v97
	v_add_f32_e32 v97, v98, v99
	s_barrier
	v_add_f32_e32 v100, v177, v100
	v_add_f32_e32 v96, v96, v97
	v_add_f32_e32 v177, v100, v96
	s_add_i32 s21, s21, 2
	s_addk_i32 s15, 0x80
	s_add_i32 s20, s20, 0x8000
	s_add_i32 s46, s20, 0xffff4000
	ds_read_b128 v[96:99], v205 offset:16384
	ds_read_b128 v[100:103], v205 offset:24576
	s_waitcnt lgkmcnt(0)
	v_mfma_f32_32x32x16_bf16 v[112:127], v[96:99], v[160:163], 0
	ds_read_b128 v[128:131], v211 offset:16384
	ds_read_b128 v[132:135], v211 offset:24576
	ds_read_b128 v[136:139], v212 offset:16384
	v_exp_f32_e32 v140, v48
	v_exp_f32_e32 v141, v49
	v_exp_f32_e32 v142, v50
	v_exp_f32_e32 v143, v51
	ds_read_b128 v[48:51], v212 offset:24576
	v_mfma_f32_32x32x16_bf16 v[96:111], v[100:103], v[160:163], 0
	v_exp_f32_e32 v144, v52
	v_exp_f32_e32 v145, v53
	v_exp_f32_e32 v146, v54
	v_exp_f32_e32 v147, v55
	s_waitcnt lgkmcnt(0)
	v_mfma_f32_32x32x16_bf16 v[112:127], v[128:131], v[164:167], v[112:127]
	ds_read_b128 v[52:55], v213 offset:16384
	v_exp_f32_e32 v148, v56
	v_exp_f32_e32 v149, v57
	v_exp_f32_e32 v150, v58
	v_exp_f32_e32 v151, v59
	v_mfma_f32_32x32x16_bf16 v[96:111], v[132:135], v[164:167], v[96:111]
	ds_read_b128 v[56:59], v213 offset:24576
	v_exp_f32_e32 v128, v60
	v_exp_f32_e32 v129, v61
	v_exp_f32_e32 v130, v62
	v_exp_f32_e32 v131, v63
	v_mfma_f32_32x32x16_bf16 v[112:127], v[136:139], v[168:171], v[112:127]
	ds_read_b128 v[60:63], v236 offset:16384
	v_exp_f32_e32 v132, v32
	v_exp_f32_e32 v133, v33
	v_exp_f32_e32 v134, v34
	v_exp_f32_e32 v135, v35
	v_mfma_f32_32x32x16_bf16 v[96:111], v[48:51], v[168:171], v[96:111]
	ds_read_b128 v[32:35], v236 offset:20480
	v_exp_f32_e32 v136, v36
	v_exp_f32_e32 v137, v37
	v_exp_f32_e32 v138, v38
	v_exp_f32_e32 v139, v39
	s_waitcnt lgkmcnt(0)
	v_mfma_f32_32x32x16_bf16 v[112:127], v[52:55], v[172:175], v[112:127]
	ds_read_b128 v[36:39], v236 offset:24576
	v_exp_f32_e32 v152, v40
	v_exp_f32_e32 v153, v41
	v_exp_f32_e32 v154, v42
	v_exp_f32_e32 v155, v43
	v_mfma_f32_32x32x16_bf16 v[96:111], v[56:59], v[172:175], v[96:111]
	ds_read_b128 v[40:43], v236 offset:28672
	v_exp_f32_e32 v156, v44
	v_exp_f32_e32 v157, v45
	v_exp_f32_e32 v158, v46
	v_exp_f32_e32 v159, v47
	v_cvt_pk_bf16_f32 v44, v140, v141
	v_cvt_pk_bf16_f32 v45, v142, v143
	v_cvt_pk_bf16_f32 v46, v144, v145
	v_cvt_pk_bf16_f32 v47, v146, v147
	s_nop 1
	v_mfma_f32_32x32x16_bf16 v[80:95], v[60:63], v[44:47], v[80:95]
	ds_read_b128 v[48:51], v237 offset:16384
	v_cvt_pk_bf16_f32 v52, v148, v149
	v_cvt_pk_bf16_f32 v53, v150, v151
	v_cvt_pk_bf16_f32 v54, v128, v129
	v_cvt_pk_bf16_f32 v55, v130, v131
	v_mfma_f32_32x32x16_bf16 v[64:79], v[32:35], v[44:47], v[64:79]
	ds_read_b128 v[56:59], v237 offset:20480
	v_pk_add_f32 v[62:63], v[146:147], v[142:143]
	v_pk_add_f32 v[60:61], v[144:145], v[140:141]
	s_waitcnt lgkmcnt(0)
	v_mfma_f32_32x32x16_bf16 v[16:31], v[36:39], v[44:47], v[16:31]
	ds_read_b128 v[32:35], v237 offset:24576
	v_add_f32_e64 v62, v150, v62
	v_add_f32_e64 v63, v151, v63
	v_add_f32_e64 v60, v148, v60
	v_add_f32_e64 v61, v149, v61
	v_pk_add_f32 v[62:63], v[130:131], v[62:63]
	v_pk_add_f32 v[60:61], v[128:129], v[60:61]
	v_mfma_f32_32x32x16_bf16 v[0:15], v[40:43], v[44:47], v[0:15]
	ds_read_b128 v[36:39], v237 offset:28672
	v_mfma_f32_32x32x16_bf16 v[80:95], v[48:51], v[52:55], v[80:95]
	ds_read_b128 v[40:43], v238 offset:16384
	v_cvt_pk_bf16_f32 v44, v132, v133
	v_cvt_pk_bf16_f32 v45, v134, v135
	v_cvt_pk_bf16_f32 v46, v136, v137
	v_cvt_pk_bf16_f32 v47, v138, v139
	v_mfma_f32_32x32x16_bf16 v[64:79], v[56:59], v[52:55], v[64:79]
	ds_read_b128 v[48:51], v238 offset:20480
	v_add_f32_e64 v62, v134, v62
	v_add_f32_e64 v63, v135, v63
	v_add_f32_e64 v60, v132, v60
	v_add_f32_e64 v61, v133, v61
	v_pk_add_f32 v[62:63], v[138:139], v[62:63]
	v_pk_add_f32 v[60:61], v[136:137], v[60:61]
	s_waitcnt lgkmcnt(0)
	v_mfma_f32_32x32x16_bf16 v[16:31], v[32:35], v[52:55], v[16:31]
	ds_read_b128 v[56:59], v238 offset:24576
	v_add_f32_e64 v62, v154, v62
	v_add_f32_e64 v63, v155, v63
	v_add_f32_e64 v60, v152, v60
	v_add_f32_e64 v61, v153, v61
	v_pk_add_f32 v[130:131], v[158:159], v[62:63]
	v_pk_add_f32 v[128:129], v[156:157], v[60:61]
	v_mfma_f32_32x32x16_bf16 v[0:15], v[36:39], v[52:55], v[0:15]
	ds_read_b128 v[32:35], v238 offset:28672
	v_mfma_f32_32x32x16_bf16 v[80:95], v[40:43], v[44:47], v[80:95]
	ds_read_b128 v[36:39], v239 offset:16384
	v_cvt_pk_bf16_f32 v52, v152, v153
	v_cvt_pk_bf16_f32 v53, v154, v155
	v_cvt_pk_bf16_f32 v54, v156, v157
	v_cvt_pk_bf16_f32 v55, v158, v159
	v_mfma_f32_32x32x16_bf16 v[64:79], v[48:51], v[44:47], v[64:79]
	ds_read_b128 v[40:43], v239 offset:20480
	s_waitcnt lgkmcnt(0)
	v_mfma_f32_32x32x16_bf16 v[16:31], v[56:59], v[44:47], v[16:31]
	ds_read_b128 v[48:51], v239 offset:24576
	v_mfma_f32_32x32x16_bf16 v[0:15], v[32:35], v[44:47], v[0:15]
	ds_read_b128 v[56:59], v239 offset:28672
	v_mfma_f32_32x32x16_bf16 v[80:95], v[36:39], v[52:55], v[80:95]
	v_mfma_f32_32x32x16_bf16 v[64:79], v[40:43], v[52:55], v[64:79]
	s_waitcnt lgkmcnt(0)
	v_mfma_f32_32x32x16_bf16 v[16:31], v[48:51], v[52:55], v[16:31]
	v_mfma_f32_32x32x16_bf16 v[0:15], v[56:59], v[52:55], v[0:15]
	s_waitcnt vmcnt(0) lgkmcnt(0)
	s_barrier
	v_exp_f32_e32 v144, v112
	ds_read_b128 v[32:35], v205 offset:32768
	ds_read_b128 v[36:39], v205 offset:40960
	s_waitcnt lgkmcnt(0)
	v_mfma_f32_32x32x16_bf16 v[48:63], v[32:35], v[160:163], 0
	ds_read_b128 v[132:135], v211 offset:32768
	ds_read_b128 v[136:139], v211 offset:40960
	ds_read_b128 v[140:143], v212 offset:32768
	v_exp_f32_e32 v145, v113
	v_exp_f32_e32 v146, v114
	v_exp_f32_e32 v147, v115
	ds_read_b128 v[112:115], v212 offset:40960
	v_mfma_f32_32x32x16_bf16 v[32:47], v[36:39], v[160:163], 0
	v_exp_f32_e32 v148, v116
	v_exp_f32_e32 v149, v117
	v_exp_f32_e32 v150, v118
	v_exp_f32_e32 v151, v119
	s_waitcnt lgkmcnt(0)
	v_mfma_f32_32x32x16_bf16 v[48:63], v[132:135], v[164:167], v[48:63]
	ds_read_b128 v[116:119], v213 offset:32768
	v_exp_f32_e32 v152, v120
	v_exp_f32_e32 v153, v121
	v_exp_f32_e32 v154, v122
	v_exp_f32_e32 v155, v123
	v_mfma_f32_32x32x16_bf16 v[32:47], v[136:139], v[164:167], v[32:47]
	ds_read_b128 v[120:123], v213 offset:40960
	v_exp_f32_e32 v156, v124
	v_exp_f32_e32 v157, v125
	v_exp_f32_e32 v158, v126
	v_exp_f32_e32 v159, v127
	v_mfma_f32_32x32x16_bf16 v[48:63], v[140:143], v[168:171], v[48:63]
	ds_read_b128 v[124:127], v236 offset:32768
	v_exp_f32_e32 v136, v96
	v_exp_f32_e32 v137, v97
	v_exp_f32_e32 v138, v98
	v_exp_f32_e32 v139, v99
	v_mfma_f32_32x32x16_bf16 v[32:47], v[112:115], v[168:171], v[32:47]
	ds_read_b128 v[96:99], v236 offset:36864
	v_exp_f32_e32 v140, v100
	v_exp_f32_e32 v141, v101
	v_exp_f32_e32 v142, v102
	v_exp_f32_e32 v143, v103
	s_waitcnt lgkmcnt(0)
	v_mfma_f32_32x32x16_bf16 v[48:63], v[116:119], v[172:175], v[48:63]
	ds_read_b128 v[100:103], v236 offset:40960
	v_exp_f32_e32 v178, v104
	v_exp_f32_e32 v179, v105
	v_exp_f32_e32 v180, v106
	v_exp_f32_e32 v181, v107
	v_mfma_f32_32x32x16_bf16 v[32:47], v[120:123], v[172:175], v[32:47]
	ds_read_b128 v[104:107], v236 offset:45056
	v_exp_f32_e32 v182, v108
	v_exp_f32_e32 v183, v109
	v_exp_f32_e32 v184, v110
	v_exp_f32_e32 v185, v111
	v_cvt_pk_bf16_f32 v108, v144, v145
	v_cvt_pk_bf16_f32 v109, v146, v147
	v_cvt_pk_bf16_f32 v110, v148, v149
	v_cvt_pk_bf16_f32 v111, v150, v151
	s_nop 1
	v_mfma_f32_32x32x16_bf16 v[80:95], v[124:127], v[108:111], v[80:95]
	ds_read_b128 v[112:115], v237 offset:32768
	v_cvt_pk_bf16_f32 v116, v152, v153
	v_cvt_pk_bf16_f32 v117, v154, v155
	v_cvt_pk_bf16_f32 v118, v156, v157
	v_cvt_pk_bf16_f32 v119, v158, v159
	v_mfma_f32_32x32x16_bf16 v[64:79], v[96:99], v[108:111], v[64:79]
	ds_read_b128 v[120:123], v237 offset:36864
	v_pk_add_f32 v[126:127], v[150:151], v[146:147]
	v_pk_add_f32 v[124:125], v[148:149], v[144:145]
	s_waitcnt lgkmcnt(0)
	v_mfma_f32_32x32x16_bf16 v[16:31], v[100:103], v[108:111], v[16:31]
	ds_read_b128 v[132:135], v237 offset:40960
	v_add_f32_e64 v98, v154, v126
	v_add_f32_e64 v99, v155, v127
	v_add_f32_e64 v96, v152, v124
	v_add_f32_e64 v97, v153, v125
	v_pk_add_f32 v[98:99], v[158:159], v[98:99]
	v_pk_add_f32 v[96:97], v[156:157], v[96:97]
	v_mfma_f32_32x32x16_bf16 v[0:15], v[104:107], v[108:111], v[0:15]
	ds_read_b128 v[100:103], v237 offset:45056
	v_mfma_f32_32x32x16_bf16 v[80:95], v[112:115], v[116:119], v[80:95]
	ds_read_b128 v[104:107], v238 offset:32768
	v_cvt_pk_bf16_f32 v108, v136, v137
	v_cvt_pk_bf16_f32 v109, v138, v139
	v_cvt_pk_bf16_f32 v110, v140, v141
	v_cvt_pk_bf16_f32 v111, v142, v143
	v_mfma_f32_32x32x16_bf16 v[64:79], v[120:123], v[116:119], v[64:79]
	ds_read_b128 v[112:115], v238 offset:36864
	v_add_f32_e64 v98, v138, v98
	v_add_f32_e64 v99, v139, v99
	v_add_f32_e64 v96, v136, v96
	v_add_f32_e64 v97, v137, v97
	v_pk_add_f32 v[98:99], v[142:143], v[98:99]
	v_pk_add_f32 v[96:97], v[140:141], v[96:97]
	s_waitcnt lgkmcnt(0)
	v_mfma_f32_32x32x16_bf16 v[16:31], v[132:135], v[116:119], v[16:31]
	ds_read_b128 v[120:123], v238 offset:40960
	v_add_f32_e64 v98, v180, v98
	v_add_f32_e64 v99, v181, v99
	v_add_f32_e64 v96, v178, v96
	v_add_f32_e64 v97, v179, v97
	v_pk_add_f32 v[98:99], v[184:185], v[98:99]
	v_pk_add_f32 v[96:97], v[182:183], v[96:97]
	v_mfma_f32_32x32x16_bf16 v[0:15], v[100:103], v[116:119], v[0:15]
	ds_read_b128 v[124:127], v238 offset:45056
	v_mfma_f32_32x32x16_bf16 v[80:95], v[104:107], v[108:111], v[80:95]
	ds_read_b128 v[100:103], v239 offset:32768
	v_cvt_pk_bf16_f32 v116, v178, v179
	v_cvt_pk_bf16_f32 v117, v180, v181
	v_cvt_pk_bf16_f32 v118, v182, v183
	v_cvt_pk_bf16_f32 v119, v184, v185
	v_mfma_f32_32x32x16_bf16 v[64:79], v[112:115], v[108:111], v[64:79]
	ds_read_b128 v[104:107], v239 offset:36864
	s_waitcnt lgkmcnt(0)
	v_mfma_f32_32x32x16_bf16 v[16:31], v[120:123], v[108:111], v[16:31]
	ds_read_b128 v[112:115], v239 offset:40960
	v_mfma_f32_32x32x16_bf16 v[0:15], v[124:127], v[108:111], v[0:15]
	ds_read_b128 v[120:123], v239 offset:45056
	v_mfma_f32_32x32x16_bf16 v[80:95], v[100:103], v[116:119], v[80:95]
	v_mfma_f32_32x32x16_bf16 v[64:79], v[104:107], v[116:119], v[64:79]
	s_waitcnt lgkmcnt(0)
	v_mfma_f32_32x32x16_bf16 v[16:31], v[112:115], v[116:119], v[16:31]
	v_mfma_f32_32x32x16_bf16 v[0:15], v[120:123], v[116:119], v[0:15]
	s_waitcnt vmcnt(0) lgkmcnt(0)
	v_add_f32_e32 v100, v128, v129
	v_add_f32_e32 v101, v130, v131
	v_add_f32_e32 v100, v100, v101
	v_add_f32_e32 v96, v96, v97
	v_add_f32_e32 v97, v98, v99
	s_barrier
	v_add_f32_e32 v100, v177, v100
	v_add_f32_e32 v96, v96, v97
	v_add_f32_e32 v177, v100, v96
	s_add_i32 s21, s21, 2
	s_addk_i32 s15, 0x80
	s_add_i32 s20, s20, 0x8000
	s_branch .LBB0_960

.Lst1_exit:
	s_cmp_lg_u32 s47, 61
	s_cbranch_scc1 .Lst1_orig
	s_cmp_lg_u32 s48, 1
	s_cbranch_scc1 .Lst1_orig
	s_and_b32 s2, s46, 0xffff
	s_cmp_lg_u32 s2, 0x0
	s_cbranch_scc1 .Lst1_orig
	s_mov_b32 s44, s21
	s_add_i32 s44, s44, s41
	s_sub_i32 s44, s44, 64
	s_mul_hi_i32 s45, s44, 0x600
	s_mulk_i32 s44, 0x600
	s_add_u32 s44, s14, s44
	s_addc_u32 s45, s15, s45
	s_add_i32 s49, s58, 0x4000
	s_mov_b32 m0, s49
	s_nop 0
	global_load_lds_dwordx4 v198, s[44:45]
	s_add_i32 m0, s49, 0x400
	s_nop 0
	global_load_lds_dwordx4 v194, s[44:45]
	s_mov_b32 s44, s40
	s_add_i32 s44, s44, s41
	s_addk_i32 s44, 0xff80
	s_ashr_i32 s45, s44, 31
	s_lshl_b64 s[44:45], s[44:45], 1
	s_add_u32 s44, s39, s44
	s_addc_u32 s45, s67, s45
	s_add_i32 s49, s46, 0xffffc000
	s_add_i32 s49, s58, 0xc000
	s_add_i32 m0, s49, 0xc000
	s_nop 0
	global_load_lds_dwordx4 v196, s[44:45]
	v_lshl_add_u64 v[140:141], s[44:45], 0, v[192:193]
	s_add_i32 m0, s49, 0xc400
	s_nop 0
	global_load_lds_dwordx4 v[140:141], off
	ds_read_b128 v[140:143], v206 offset:49152
	ds_read_b128 v[148:151], v206 offset:53248
	ds_read_b128 v[152:155], v206 offset:57344
	ds_read_b128 v[156:159], v206 offset:61440
	s_waitcnt lgkmcnt(0)
	v_mfma_f32_32x32x16_bf16 v[80:95], v[140:143], v[144:147], v[80:95]
	ds_read_b128 v[140:143], v207 offset:49152
	v_mfma_f32_32x32x16_bf16 v[64:79], v[148:151], v[144:147], v[64:79]
	ds_read_b128 v[148:151], v207 offset:53248
	v_mfma_f32_32x32x16_bf16 v[16:31], v[152:155], v[144:147], v[16:31]
	ds_read_b128 v[152:155], v207 offset:57344
	v_mfma_f32_32x32x16_bf16 v[0:15], v[156:159], v[144:147], v[0:15]
	ds_read_b128 v[144:147], v207 offset:61440
	s_waitcnt lgkmcnt(0)
	v_mfma_f32_32x32x16_bf16 v[80:95], v[140:143], v[128:131], v[80:95]
	ds_read_b128 v[140:143], v208 offset:49152
	v_mfma_f32_32x32x16_bf16 v[64:79], v[148:151], v[128:131], v[64:79]
	ds_read_b128 v[148:151], v208 offset:53248
	v_mfma_f32_32x32x16_bf16 v[16:31], v[152:155], v[128:131], v[16:31]
	ds_read_b128 v[152:155], v208 offset:57344
	v_mfma_f32_32x32x16_bf16 v[0:15], v[144:147], v[128:131], v[0:15]
	ds_read_b128 v[128:131], v208 offset:61440
	s_waitcnt lgkmcnt(0)
	v_mfma_f32_32x32x16_bf16 v[80:95], v[140:143], v[132:135], v[80:95]
	ds_read_b128 v[140:143], v209 offset:49152
	v_mfma_f32_32x32x16_bf16 v[64:79], v[148:151], v[132:135], v[64:79]
	ds_read_b128 v[144:147], v209 offset:53248
	v_mfma_f32_32x32x16_bf16 v[16:31], v[152:155], v[132:135], v[16:31]
	ds_read_b128 v[148:151], v209 offset:57344
	v_mfma_f32_32x32x16_bf16 v[0:15], v[128:131], v[132:135], v[0:15]
	ds_read_b128 v[128:131], v209 offset:61440
	s_waitcnt lgkmcnt(0)
	v_mfma_f32_32x32x16_bf16 v[80:95], v[140:143], v[136:139], v[80:95]
	ds_read_b128 v[132:135], v205 offset:32768
	v_mfma_f32_32x32x16_bf16 v[64:79], v[144:147], v[136:139], v[64:79]
	ds_read_b128 v[140:143], v205 offset:40960
	v_mfma_f32_32x32x16_bf16 v[16:31], v[148:151], v[136:139], v[16:31]
	ds_read_b128 v[176:179], v211 offset:32768
	v_mfma_f32_32x32x16_bf16 v[0:15], v[128:131], v[136:139], v[0:15]
	ds_read_b128 v[182:185], v211 offset:40960
	s_waitcnt lgkmcnt(0)
	v_mfma_f32_32x32x16_bf16 v[144:159], v[132:135], v[160:163], 0
	ds_read_b128 v[186:189], v212 offset:32768
	v_exp_f32_e32 v220, v112
	v_exp_f32_e32 v221, v113
	v_exp_f32_e32 v222, v114
	v_exp_f32_e32 v223, v115
	v_mfma_f32_32x32x16_bf16 v[128:143], v[140:143], v[160:163], 0
	ds_read_b128 v[216:219], v212 offset:40960
	v_exp_f32_e32 v224, v116
	v_exp_f32_e32 v225, v117
	v_exp_f32_e32 v226, v118
	v_exp_f32_e32 v227, v119
	v_mfma_f32_32x32x16_bf16 v[144:159], v[176:179], v[164:167], v[144:159]
	ds_read_b128 v[116:119], v213 offset:32768
	v_exp_f32_e32 v228, v120
	v_exp_f32_e32 v229, v121
	v_exp_f32_e32 v230, v122
	v_exp_f32_e32 v231, v123
	v_cvt_pk_bf16_f32 v112, v220, v221
	v_cvt_pk_bf16_f32 v113, v222, v223
	v_cvt_pk_bf16_f32 v114, v224, v225
	v_cvt_pk_bf16_f32 v115, v226, v227
	v_pk_add_f32 v[122:123], v[226:227], v[222:223]
	v_pk_add_f32 v[120:121], v[224:225], v[220:221]
	v_mfma_f32_32x32x16_bf16 v[128:143], v[182:185], v[164:167], v[128:143]
	ds_read_b128 v[176:179], v213 offset:40960
	v_exp_f32_e32 v124, v124
	v_exp_f32_e32 v125, v125
	v_exp_f32_e32 v126, v126
	v_exp_f32_e32 v127, v127
	s_waitcnt lgkmcnt(0)
	v_mfma_f32_32x32x16_bf16 v[144:159], v[186:189], v[168:171], v[144:159]
	v_add_f32_e64 v122, v230, v122
	v_add_f32_e64 v123, v231, v123
	v_add_f32_e64 v120, v228, v120
	v_add_f32_e64 v121, v229, v121
	v_exp_f32_e32 v182, v96
	v_exp_f32_e32 v183, v97
	v_exp_f32_e32 v184, v98
	v_exp_f32_e32 v185, v99
	v_cvt_pk_bf16_f32 v96, v228, v229
	v_cvt_pk_bf16_f32 v97, v230, v231
	v_cvt_pk_bf16_f32 v98, v124, v125
	v_cvt_pk_bf16_f32 v99, v126, v127
	v_pk_add_f32 v[122:123], v[126:127], v[122:123]
	v_pk_add_f32 v[120:121], v[124:125], v[120:121]
	v_mfma_f32_32x32x16_bf16 v[128:143], v[216:219], v[168:171], v[128:143]
	v_exp_f32_e32 v124, v100
	v_exp_f32_e32 v125, v101
	v_exp_f32_e32 v126, v102
	v_exp_f32_e32 v127, v103
	v_mfma_f32_32x32x16_bf16 v[144:159], v[116:119], v[172:175], v[144:159]
	v_exp_f32_e32 v186, v104
	v_exp_f32_e32 v187, v105
	v_exp_f32_e32 v188, v106
	v_exp_f32_e32 v189, v107
	v_pk_add_f32 v[106:107], v[184:185], v[122:123]
	v_pk_add_f32 v[104:105], v[182:183], v[120:121]
	v_cvt_pk_bf16_f32 v100, v182, v183
	v_cvt_pk_bf16_f32 v101, v184, v185
	v_cvt_pk_bf16_f32 v102, v124, v125
	v_cvt_pk_bf16_f32 v103, v126, v127
	v_pk_add_f32 v[118:119], v[126:127], v[106:107]
	v_pk_add_f32 v[116:117], v[124:125], v[104:105]
	v_mfma_f32_32x32x16_bf16 v[128:143], v[176:179], v[172:175], v[128:143]
	v_exp_f32_e32 v120, v108
	v_exp_f32_e32 v121, v109
	v_exp_f32_e32 v122, v110
	v_exp_f32_e32 v123, v111
	v_pk_add_f32 v[110:111], v[188:189], v[118:119]
	v_pk_add_f32 v[108:109], v[186:187], v[116:117]
	v_cvt_pk_bf16_f32 v104, v186, v187
	v_cvt_pk_bf16_f32 v105, v188, v189
	v_cvt_pk_bf16_f32 v106, v120, v121
	v_cvt_pk_bf16_f32 v107, v122, v123
	v_pk_add_f32 v[178:179], v[122:123], v[110:111]
	v_pk_add_f32 v[176:177], v[120:121], v[108:109]
	s_waitcnt vmcnt(4) lgkmcnt(0)
	s_barrier
	s_mov_b32 s69, s21
	s_add_i32 s69, s69, s41
	s_mul_hi_i32 s71, s69, 0x600
	s_mulk_i32 s69, 0x600
	s_add_u32 s70, s14, s69
	s_addc_u32 s71, s15, s71
	s_add_i32 s68, 0x8000, s57
	s_mov_b32 m0, s68
	s_nop 0
	global_load_lds_dwordx4 v198, s[70:71]
	s_add_i32 m0, s68, 0x400
	s_nop 0
	global_load_lds_dwordx4 v194, s[70:71]
	s_mov_b32 s2, s21
	s_add_i32 s2, s2, s41
	s_sub_i32 s2, s2, 64
	s_ashr_i32 s3, s2, 31
	s_lshl_b64 s[2:3], s[2:3], 1
	s_add_u32 s2, s39, s2
	s_addc_u32 s3, s67, s3
	s_add_i32 s49, s58, 0
	s_add_i32 m0, s49, 0xc000
	s_nop 0
	global_load_lds_dwordx4 v196, s[2:3]
	s_add_i32 m0, s49, 0xc400
	s_nop 0
	global_load_lds_dwordx4 v192, s[2:3]
	s_add_i32 s2, s46, 0xffff4000
	ds_read_b128 v[108:111], v236
	ds_read_b128 v[116:119], v236 offset:4096
	ds_read_b128 v[120:123], v236 offset:8192
	ds_read_b128 v[124:127], v236 offset:12288
	s_waitcnt lgkmcnt(0)
	v_mfma_f32_32x32x16_bf16 v[80:95], v[108:111], v[112:115], v[80:95]
	ds_read_b128 v[108:111], v237
	v_mfma_f32_32x32x16_bf16 v[64:79], v[116:119], v[112:115], v[64:79]
	ds_read_b128 v[116:119], v237 offset:4096
	v_mfma_f32_32x32x16_bf16 v[16:31], v[120:123], v[112:115], v[16:31]
	ds_read_b128 v[120:123], v237 offset:8192
	v_mfma_f32_32x32x16_bf16 v[0:15], v[124:127], v[112:115], v[0:15]
	ds_read_b128 v[112:115], v237 offset:12288
	s_waitcnt lgkmcnt(0)
	v_mfma_f32_32x32x16_bf16 v[80:95], v[108:111], v[96:99], v[80:95]
	ds_read_b128 v[108:111], v238
	v_mfma_f32_32x32x16_bf16 v[64:79], v[116:119], v[96:99], v[64:79]
	ds_read_b128 v[116:119], v238 offset:4096
	v_mfma_f32_32x32x16_bf16 v[16:31], v[120:123], v[96:99], v[16:31]
	ds_read_b128 v[120:123], v238 offset:8192
	v_mfma_f32_32x32x16_bf16 v[0:15], v[112:115], v[96:99], v[0:15]
	ds_read_b128 v[96:99], v238 offset:12288
	s_waitcnt lgkmcnt(0)
	v_mfma_f32_32x32x16_bf16 v[80:95], v[108:111], v[100:103], v[80:95]
	ds_read_b128 v[108:111], v239
	v_mfma_f32_32x32x16_bf16 v[64:79], v[116:119], v[100:103], v[64:79]
	ds_read_b128 v[112:115], v239 offset:4096
	v_mfma_f32_32x32x16_bf16 v[16:31], v[120:123], v[100:103], v[16:31]
	ds_read_b128 v[116:119], v239 offset:8192
	v_mfma_f32_32x32x16_bf16 v[0:15], v[96:99], v[100:103], v[0:15]
	ds_read_b128 v[120:123], v239 offset:12288
	s_waitcnt lgkmcnt(0)
	v_mfma_f32_32x32x16_bf16 v[80:95], v[108:111], v[104:107], v[80:95]
	ds_read_b128 v[96:99], v205
	v_mfma_f32_32x32x16_bf16 v[64:79], v[112:115], v[104:107], v[64:79]
	ds_read_b128 v[100:103], v205 offset:8192
	v_mfma_f32_32x32x16_bf16 v[16:31], v[116:119], v[104:107], v[16:31]
	ds_read_b128 v[182:185], v211
	v_mfma_f32_32x32x16_bf16 v[0:15], v[120:123], v[104:107], v[0:15]
	ds_read_b128 v[186:189], v211 offset:8192
	s_waitcnt lgkmcnt(0)
	v_mfma_f32_32x32x16_bf16 v[112:127], v[96:99], v[160:163], 0
	ds_read_b128 v[216:219], v212
	v_exp_f32_e32 v224, v144
	v_exp_f32_e32 v225, v145
	v_exp_f32_e32 v226, v146
	v_exp_f32_e32 v227, v147
	ds_read_b128 v[220:223], v212 offset:8192
	v_mfma_f32_32x32x16_bf16 v[96:111], v[100:103], v[160:163], 0
	v_exp_f32_e32 v228, v148
	v_exp_f32_e32 v229, v149
	v_exp_f32_e32 v230, v150
	v_exp_f32_e32 v231, v151
	v_mfma_f32_32x32x16_bf16 v[112:127], v[182:185], v[164:167], v[112:127]
	ds_read_b128 v[148:151], v213
	v_exp_f32_e32 v232, v152
	v_exp_f32_e32 v233, v153
	v_exp_f32_e32 v234, v154
	v_exp_f32_e32 v235, v155
	v_cvt_pk_bf16_f32 v144, v224, v225
	v_cvt_pk_bf16_f32 v145, v226, v227
	v_cvt_pk_bf16_f32 v146, v228, v229
	v_cvt_pk_bf16_f32 v147, v230, v231
	v_pk_add_f32 v[154:155], v[230:231], v[226:227]
	v_pk_add_f32 v[152:153], v[228:229], v[224:225]
	v_mfma_f32_32x32x16_bf16 v[96:111], v[186:189], v[164:167], v[96:111]
	ds_read_b128 v[182:185], v213 offset:8192
	v_exp_f32_e32 v156, v156
	v_exp_f32_e32 v157, v157
	v_exp_f32_e32 v158, v158
	v_exp_f32_e32 v159, v159
	s_waitcnt lgkmcnt(0)
	v_mfma_f32_32x32x16_bf16 v[112:127], v[216:219], v[168:171], v[112:127]
	v_add_f32_e64 v154, v234, v154
	v_add_f32_e64 v155, v235, v155
	v_add_f32_e64 v152, v232, v152
	v_add_f32_e64 v153, v233, v153
	v_exp_f32_e32 v186, v128
	v_exp_f32_e32 v187, v129
	v_exp_f32_e32 v188, v130
	v_exp_f32_e32 v189, v131
	v_cvt_pk_bf16_f32 v128, v232, v233
	v_cvt_pk_bf16_f32 v129, v234, v235
	v_cvt_pk_bf16_f32 v130, v156, v157
	v_cvt_pk_bf16_f32 v131, v158, v159
	v_pk_add_f32 v[154:155], v[158:159], v[154:155]
	v_pk_add_f32 v[152:153], v[156:157], v[152:153]
	v_mfma_f32_32x32x16_bf16 v[96:111], v[220:223], v[168:171], v[96:111]
	v_exp_f32_e32 v156, v132
	v_exp_f32_e32 v157, v133
	v_exp_f32_e32 v158, v134
	v_exp_f32_e32 v159, v135
	v_mfma_f32_32x32x16_bf16 v[112:127], v[148:151], v[172:175], v[112:127]
	v_exp_f32_e32 v216, v136
	v_exp_f32_e32 v217, v137
	v_exp_f32_e32 v218, v138
	v_exp_f32_e32 v219, v139
	v_pk_add_f32 v[138:139], v[188:189], v[154:155]
	v_pk_add_f32 v[136:137], v[186:187], v[152:153]
	v_cvt_pk_bf16_f32 v132, v186, v187
	v_cvt_pk_bf16_f32 v133, v188, v189
	v_cvt_pk_bf16_f32 v134, v156, v157
	v_cvt_pk_bf16_f32 v135, v158, v159
	v_pk_add_f32 v[150:151], v[158:159], v[138:139]
	v_pk_add_f32 v[148:149], v[156:157], v[136:137]
	v_mfma_f32_32x32x16_bf16 v[96:111], v[182:185], v[172:175], v[96:111]
	v_exp_f32_e32 v152, v140
	v_exp_f32_e32 v153, v141
	v_exp_f32_e32 v154, v142
	v_exp_f32_e32 v155, v143
	v_pk_add_f32 v[142:143], v[218:219], v[150:151]
	v_pk_add_f32 v[140:141], v[216:217], v[148:149]
	v_cvt_pk_bf16_f32 v136, v216, v217
	v_cvt_pk_bf16_f32 v137, v218, v219
	v_cvt_pk_bf16_f32 v138, v152, v153
	v_cvt_pk_bf16_f32 v139, v154, v155
	v_pk_add_f32 v[142:143], v[154:155], v[142:143]
	v_pk_add_f32 v[140:141], v[152:153], v[140:141]
	s_waitcnt vmcnt(4) lgkmcnt(0)
	v_add_f32_e32 v148, v176, v177
	v_add_f32_e32 v149, v178, v179
	v_add_f32_e32 v148, v148, v149
	v_add_f32_e32 v140, v140, v141
	v_add_f32_e32 v141, v142, v143
	s_barrier
	v_add_f32_e32 v148, v180, v148
	v_add_f32_e32 v140, v140, v141
	v_add_f32_e32 v180, v148, v140
	s_add_i32 s47, s47, 2
	s_addk_i32 s41, 0x80
	s_add_i32 s46, s46, 0x8000
	s_mov_b32 s44, s21
	s_add_i32 s44, s44, s41
	s_sub_i32 s44, s44, 64
	s_mul_hi_i32 s45, s44, 0x600
	s_mulk_i32 s44, 0x600
	s_add_u32 s44, s14, s44
	s_addc_u32 s45, s15, s45
	s_add_i32 s49, s58, 0
	s_mov_b32 m0, s49
	s_nop 0
	global_load_lds_dwordx4 v198, s[44:45]
	s_add_i32 m0, s49, 0x400
	s_nop 0
	global_load_lds_dwordx4 v194, s[44:45]
	s_mov_b32 s44, s21
	s_add_i32 s44, s44, s41
	s_addk_i32 s44, 0xff80
	s_ashr_i32 s45, s44, 31
	s_lshl_b64 s[44:45], s[44:45], 1
	s_add_u32 s44, s39, s44
	s_addc_u32 s45, s67, s45
	s_add_i32 s49, s46, 0xffffc000
	s_add_i32 s49, s58, 0x4000
	s_add_i32 m0, s49, 0xc000
	s_nop 0
	global_load_lds_dwordx4 v196, s[44:45]
	v_lshl_add_u64 v[140:141], s[44:45], 0, v[192:193]
	s_add_i32 m0, s49, 0xc400
	s_nop 0
	global_load_lds_dwordx4 v[140:141], off
	ds_read_b128 v[140:143], v236 offset:16384
	ds_read_b128 v[148:151], v236 offset:20480
	ds_read_b128 v[152:155], v236 offset:24576
	ds_read_b128 v[156:159], v236 offset:28672
	s_waitcnt lgkmcnt(0)
	v_mfma_f32_32x32x16_bf16 v[80:95], v[140:143], v[144:147], v[80:95]
	ds_read_b128 v[140:143], v237 offset:16384
	v_mfma_f32_32x32x16_bf16 v[64:79], v[148:151], v[144:147], v[64:79]
	ds_read_b128 v[148:151], v237 offset:20480
	v_mfma_f32_32x32x16_bf16 v[16:31], v[152:155], v[144:147], v[16:31]
	ds_read_b128 v[152:155], v237 offset:24576
	v_mfma_f32_32x32x16_bf16 v[0:15], v[156:159], v[144:147], v[0:15]
	ds_read_b128 v[144:147], v237 offset:28672
	s_waitcnt lgkmcnt(0)
	v_mfma_f32_32x32x16_bf16 v[80:95], v[140:143], v[128:131], v[80:95]
	ds_read_b128 v[140:143], v238 offset:16384
	v_mfma_f32_32x32x16_bf16 v[64:79], v[148:151], v[128:131], v[64:79]
	ds_read_b128 v[148:151], v238 offset:20480
	v_mfma_f32_32x32x16_bf16 v[16:31], v[152:155], v[128:131], v[16:31]
	ds_read_b128 v[152:155], v238 offset:24576
	v_mfma_f32_32x32x16_bf16 v[0:15], v[144:147], v[128:131], v[0:15]
	ds_read_b128 v[128:131], v238 offset:28672
	s_waitcnt lgkmcnt(0)
	v_mfma_f32_32x32x16_bf16 v[80:95], v[140:143], v[132:135], v[80:95]
	ds_read_b128 v[140:143], v239 offset:16384
	v_mfma_f32_32x32x16_bf16 v[64:79], v[148:151], v[132:135], v[64:79]
	ds_read_b128 v[144:147], v239 offset:20480
	v_mfma_f32_32x32x16_bf16 v[16:31], v[152:155], v[132:135], v[16:31]
	ds_read_b128 v[148:151], v239 offset:24576
	v_mfma_f32_32x32x16_bf16 v[0:15], v[128:131], v[132:135], v[0:15]
	ds_read_b128 v[128:131], v239 offset:28672
	s_waitcnt lgkmcnt(0)
	v_mfma_f32_32x32x16_bf16 v[80:95], v[140:143], v[136:139], v[80:95]
	ds_read_b128 v[132:135], v205 offset:16384
	v_mfma_f32_32x32x16_bf16 v[64:79], v[144:147], v[136:139], v[64:79]
	ds_read_b128 v[140:143], v205 offset:24576
	v_mfma_f32_32x32x16_bf16 v[16:31], v[148:151], v[136:139], v[16:31]
	ds_read_b128 v[176:179], v211 offset:16384
	v_mfma_f32_32x32x16_bf16 v[0:15], v[128:131], v[136:139], v[0:15]
	ds_read_b128 v[182:185], v211 offset:24576
	s_waitcnt lgkmcnt(0)
	v_mfma_f32_32x32x16_bf16 v[144:159], v[132:135], v[160:163], 0
	ds_read_b128 v[186:189], v212 offset:16384
	v_exp_f32_e32 v220, v112
	v_exp_f32_e32 v221, v113
	v_exp_f32_e32 v222, v114
	v_exp_f32_e32 v223, v115
	v_mfma_f32_32x32x16_bf16 v[128:143], v[140:143], v[160:163], 0
	ds_read_b128 v[216:219], v212 offset:24576
	v_exp_f32_e32 v224, v116
	v_exp_f32_e32 v225, v117
	v_exp_f32_e32 v226, v118
	v_exp_f32_e32 v227, v119
	v_mfma_f32_32x32x16_bf16 v[144:159], v[176:179], v[164:167], v[144:159]
	ds_read_b128 v[116:119], v213 offset:16384
	v_exp_f32_e32 v228, v120
	v_exp_f32_e32 v229, v121
	v_exp_f32_e32 v230, v122
	v_exp_f32_e32 v231, v123
	v_cvt_pk_bf16_f32 v112, v220, v221
	v_cvt_pk_bf16_f32 v113, v222, v223
	v_cvt_pk_bf16_f32 v114, v224, v225
	v_cvt_pk_bf16_f32 v115, v226, v227
	v_pk_add_f32 v[122:123], v[226:227], v[222:223]
	v_pk_add_f32 v[120:121], v[224:225], v[220:221]
	v_mfma_f32_32x32x16_bf16 v[128:143], v[182:185], v[164:167], v[128:143]
	ds_read_b128 v[176:179], v213 offset:24576
	v_exp_f32_e32 v124, v124
	v_exp_f32_e32 v125, v125
	v_exp_f32_e32 v126, v126
	v_exp_f32_e32 v127, v127
	s_waitcnt lgkmcnt(0)
	v_mfma_f32_32x32x16_bf16 v[144:159], v[186:189], v[168:171], v[144:159]
	v_add_f32_e64 v122, v230, v122
	v_add_f32_e64 v123, v231, v123
	v_add_f32_e64 v120, v228, v120
	v_add_f32_e64 v121, v229, v121
	v_exp_f32_e32 v182, v96
	v_exp_f32_e32 v183, v97
	v_exp_f32_e32 v184, v98
	v_exp_f32_e32 v185, v99
	v_cvt_pk_bf16_f32 v96, v228, v229
	v_cvt_pk_bf16_f32 v97, v230, v231
	v_cvt_pk_bf16_f32 v98, v124, v125
	v_cvt_pk_bf16_f32 v99, v126, v127
	v_pk_add_f32 v[122:123], v[126:127], v[122:123]
	v_pk_add_f32 v[120:121], v[124:125], v[120:121]
	v_mfma_f32_32x32x16_bf16 v[128:143], v[216:219], v[168:171], v[128:143]
	v_exp_f32_e32 v124, v100
	v_exp_f32_e32 v125, v101
	v_exp_f32_e32 v126, v102
	v_exp_f32_e32 v127, v103
	v_mfma_f32_32x32x16_bf16 v[144:159], v[116:119], v[172:175], v[144:159]
	v_exp_f32_e32 v186, v104
	v_exp_f32_e32 v187, v105
	v_exp_f32_e32 v188, v106
	v_exp_f32_e32 v189, v107
	v_pk_add_f32 v[106:107], v[184:185], v[122:123]
	v_pk_add_f32 v[104:105], v[182:183], v[120:121]
	v_cvt_pk_bf16_f32 v100, v182, v183
	v_cvt_pk_bf16_f32 v101, v184, v185
	v_cvt_pk_bf16_f32 v102, v124, v125
	v_cvt_pk_bf16_f32 v103, v126, v127
	v_pk_add_f32 v[118:119], v[126:127], v[106:107]
	v_pk_add_f32 v[116:117], v[124:125], v[104:105]
	v_mfma_f32_32x32x16_bf16 v[128:143], v[176:179], v[172:175], v[128:143]
	v_exp_f32_e32 v120, v108
	v_exp_f32_e32 v121, v109
	v_exp_f32_e32 v122, v110
	v_exp_f32_e32 v123, v111
	v_pk_add_f32 v[110:111], v[188:189], v[118:119]
	v_pk_add_f32 v[108:109], v[186:187], v[116:117]
	v_cvt_pk_bf16_f32 v104, v186, v187
	v_cvt_pk_bf16_f32 v105, v188, v189
	v_cvt_pk_bf16_f32 v106, v120, v121
	v_cvt_pk_bf16_f32 v107, v122, v123
	v_pk_add_f32 v[178:179], v[122:123], v[110:111]
	v_pk_add_f32 v[176:177], v[120:121], v[108:109]
	s_waitcnt vmcnt(4) lgkmcnt(0)
	s_barrier
	s_mov_b32 s69, s21
	s_add_i32 s69, s69, s41
	s_mul_hi_i32 s71, s69, 0x600
	s_mulk_i32 s69, 0x600
	s_add_u32 s70, s14, s69
	s_addc_u32 s71, s15, s71
	s_add_i32 s68, 0x4000, s57
	s_mov_b32 m0, s68
	s_nop 0
	global_load_lds_dwordx4 v198, s[70:71]
	s_add_i32 m0, s68, 0x400
	s_nop 0
	global_load_lds_dwordx4 v194, s[70:71]
	s_mov_b32 s2, s21
	s_add_i32 s2, s2, s41
	s_sub_i32 s2, s2, 64
	s_ashr_i32 s3, s2, 31
	s_lshl_b64 s[2:3], s[2:3], 1
	s_add_u32 s2, s39, s2
	s_addc_u32 s3, s67, s3
	s_add_i32 s49, s58, 0x8000
	s_add_i32 m0, s49, 0xc000
	s_nop 0
	global_load_lds_dwordx4 v196, s[2:3]
	s_add_i32 m0, s49, 0xc400
	s_nop 0
	global_load_lds_dwordx4 v192, s[2:3]
	s_add_i32 s2, s46, 0xffff4000
	ds_read_b128 v[108:111], v236 offset:32768
	ds_read_b128 v[116:119], v236 offset:36864
	ds_read_b128 v[120:123], v236 offset:40960
	ds_read_b128 v[124:127], v236 offset:45056
	s_waitcnt lgkmcnt(0)
	v_mfma_f32_32x32x16_bf16 v[80:95], v[108:111], v[112:115], v[80:95]
	ds_read_b128 v[108:111], v237 offset:32768
	v_mfma_f32_32x32x16_bf16 v[64:79], v[116:119], v[112:115], v[64:79]
	ds_read_b128 v[116:119], v237 offset:36864
	v_mfma_f32_32x32x16_bf16 v[16:31], v[120:123], v[112:115], v[16:31]
	ds_read_b128 v[120:123], v237 offset:40960
	v_mfma_f32_32x32x16_bf16 v[0:15], v[124:127], v[112:115], v[0:15]
	ds_read_b128 v[112:115], v237 offset:45056
	s_waitcnt lgkmcnt(0)
	v_mfma_f32_32x32x16_bf16 v[80:95], v[108:111], v[96:99], v[80:95]
	ds_read_b128 v[108:111], v238 offset:32768
	v_mfma_f32_32x32x16_bf16 v[64:79], v[116:119], v[96:99], v[64:79]
	ds_read_b128 v[116:119], v238 offset:36864
	v_mfma_f32_32x32x16_bf16 v[16:31], v[120:123], v[96:99], v[16:31]
	ds_read_b128 v[120:123], v238 offset:40960
	v_mfma_f32_32x32x16_bf16 v[0:15], v[112:115], v[96:99], v[0:15]
	ds_read_b128 v[96:99], v238 offset:45056
	s_waitcnt lgkmcnt(0)
	v_mfma_f32_32x32x16_bf16 v[80:95], v[108:111], v[100:103], v[80:95]
	ds_read_b128 v[108:111], v239 offset:32768
	v_mfma_f32_32x32x16_bf16 v[64:79], v[116:119], v[100:103], v[64:79]
	ds_read_b128 v[112:115], v239 offset:36864
	v_mfma_f32_32x32x16_bf16 v[16:31], v[120:123], v[100:103], v[16:31]
	ds_read_b128 v[116:119], v239 offset:40960
	v_mfma_f32_32x32x16_bf16 v[0:15], v[96:99], v[100:103], v[0:15]
	ds_read_b128 v[120:123], v239 offset:45056
	s_waitcnt lgkmcnt(0)
	v_mfma_f32_32x32x16_bf16 v[80:95], v[108:111], v[104:107], v[80:95]
	ds_read_b128 v[96:99], v205 offset:32768
	v_mfma_f32_32x32x16_bf16 v[64:79], v[112:115], v[104:107], v[64:79]
	ds_read_b128 v[100:103], v205 offset:40960
	v_mfma_f32_32x32x16_bf16 v[16:31], v[116:119], v[104:107], v[16:31]
	ds_read_b128 v[182:185], v211 offset:32768
	v_mfma_f32_32x32x16_bf16 v[0:15], v[120:123], v[104:107], v[0:15]
	ds_read_b128 v[186:189], v211 offset:40960
	s_waitcnt lgkmcnt(0)
	v_mfma_f32_32x32x16_bf16 v[112:127], v[96:99], v[160:163], 0
	ds_read_b128 v[216:219], v212 offset:32768
	v_exp_f32_e32 v224, v144
	v_exp_f32_e32 v225, v145
	v_exp_f32_e32 v226, v146
	v_exp_f32_e32 v227, v147
	ds_read_b128 v[220:223], v212 offset:40960
	v_mfma_f32_32x32x16_bf16 v[96:111], v[100:103], v[160:163], 0
	v_exp_f32_e32 v228, v148
	v_exp_f32_e32 v229, v149
	v_exp_f32_e32 v230, v150
	v_exp_f32_e32 v231, v151
	v_mfma_f32_32x32x16_bf16 v[112:127], v[182:185], v[164:167], v[112:127]
	ds_read_b128 v[148:151], v213 offset:32768
	v_exp_f32_e32 v232, v152
	v_exp_f32_e32 v233, v153
	v_exp_f32_e32 v234, v154
	v_exp_f32_e32 v235, v155
	v_cvt_pk_bf16_f32 v144, v224, v225
	v_cvt_pk_bf16_f32 v145, v226, v227
	v_cvt_pk_bf16_f32 v146, v228, v229
	v_cvt_pk_bf16_f32 v147, v230, v231
	v_pk_add_f32 v[154:155], v[230:231], v[226:227]
	v_pk_add_f32 v[152:153], v[228:229], v[224:225]
	v_mfma_f32_32x32x16_bf16 v[96:111], v[186:189], v[164:167], v[96:111]
	ds_read_b128 v[182:185], v213 offset:40960
	v_exp_f32_e32 v156, v156
	v_exp_f32_e32 v157, v157
	v_exp_f32_e32 v158, v158
	v_exp_f32_e32 v159, v159
	s_waitcnt lgkmcnt(0)
	v_mfma_f32_32x32x16_bf16 v[112:127], v[216:219], v[168:171], v[112:127]
	v_add_f32_e64 v154, v234, v154
	v_add_f32_e64 v155, v235, v155
	v_add_f32_e64 v152, v232, v152
	v_add_f32_e64 v153, v233, v153
	v_exp_f32_e32 v186, v128
	v_exp_f32_e32 v187, v129
	v_exp_f32_e32 v188, v130
	v_exp_f32_e32 v189, v131
	v_cvt_pk_bf16_f32 v128, v232, v233
	v_cvt_pk_bf16_f32 v129, v234, v235
	v_cvt_pk_bf16_f32 v130, v156, v157
	v_cvt_pk_bf16_f32 v131, v158, v159
	v_pk_add_f32 v[154:155], v[158:159], v[154:155]
	v_pk_add_f32 v[152:153], v[156:157], v[152:153]
	v_mfma_f32_32x32x16_bf16 v[96:111], v[220:223], v[168:171], v[96:111]
	v_exp_f32_e32 v156, v132
	v_exp_f32_e32 v157, v133
	v_exp_f32_e32 v158, v134
	v_exp_f32_e32 v159, v135
	v_mfma_f32_32x32x16_bf16 v[112:127], v[148:151], v[172:175], v[112:127]
	v_exp_f32_e32 v216, v136
	v_exp_f32_e32 v217, v137
	v_exp_f32_e32 v218, v138
	v_exp_f32_e32 v219, v139
	v_pk_add_f32 v[138:139], v[188:189], v[154:155]
	v_pk_add_f32 v[136:137], v[186:187], v[152:153]
	v_cvt_pk_bf16_f32 v132, v186, v187
	v_cvt_pk_bf16_f32 v133, v188, v189
	v_cvt_pk_bf16_f32 v134, v156, v157
	v_cvt_pk_bf16_f32 v135, v158, v159
	v_pk_add_f32 v[150:151], v[158:159], v[138:139]
	v_pk_add_f32 v[148:149], v[156:157], v[136:137]
	v_mfma_f32_32x32x16_bf16 v[96:111], v[182:185], v[172:175], v[96:111]
	v_exp_f32_e32 v152, v140
	v_exp_f32_e32 v153, v141
	v_exp_f32_e32 v154, v142
	v_exp_f32_e32 v155, v143
	v_pk_add_f32 v[142:143], v[218:219], v[150:151]
	v_pk_add_f32 v[140:141], v[216:217], v[148:149]
	v_cvt_pk_bf16_f32 v136, v216, v217
	v_cvt_pk_bf16_f32 v137, v218, v219
	v_cvt_pk_bf16_f32 v138, v152, v153
	v_cvt_pk_bf16_f32 v139, v154, v155
	v_pk_add_f32 v[142:143], v[154:155], v[142:143]
	v_pk_add_f32 v[140:141], v[152:153], v[140:141]
	s_waitcnt vmcnt(4) lgkmcnt(0)
	v_add_f32_e32 v148, v176, v177
	v_add_f32_e32 v149, v178, v179
	v_add_f32_e32 v148, v148, v149
	v_add_f32_e32 v140, v140, v141
	v_add_f32_e32 v141, v142, v143
	s_barrier
	v_add_f32_e32 v148, v180, v148
	v_add_f32_e32 v140, v140, v141
	v_add_f32_e32 v180, v148, v140
	s_add_i32 s47, s47, 2
	s_addk_i32 s41, 0x80
	s_add_i32 s46, s46, 0x8000
	s_mov_b32 s44, s21
	s_add_i32 s44, s44, s41
	s_addk_i32 s44, 0xff80
	s_ashr_i32 s45, s44, 31
	s_lshl_b64 s[44:45], s[44:45], 1
	s_add_u32 s44, s39, s44
	s_addc_u32 s45, s67, s45
	s_add_i32 s49, s46, 0xffffc000
	s_add_i32 s49, s58, 0xc000
	s_add_i32 m0, s49, 0xc000
	s_nop 0
	global_load_lds_dwordx4 v196, s[44:45]
	v_lshl_add_u64 v[140:141], s[44:45], 0, v[192:193]
	s_add_i32 m0, s49, 0xc400
	s_nop 0
	global_load_lds_dwordx4 v[140:141], off
	ds_read_b128 v[140:143], v206 offset:49152
	ds_read_b128 v[148:151], v206 offset:53248
	ds_read_b128 v[152:155], v206 offset:57344
	ds_read_b128 v[156:159], v206 offset:61440
	s_waitcnt lgkmcnt(0)
	v_mfma_f32_32x32x16_bf16 v[80:95], v[140:143], v[144:147], v[80:95]
	ds_read_b128 v[140:143], v207 offset:49152
	v_mfma_f32_32x32x16_bf16 v[64:79], v[148:151], v[144:147], v[64:79]
	ds_read_b128 v[148:151], v207 offset:53248
	v_mfma_f32_32x32x16_bf16 v[16:31], v[152:155], v[144:147], v[16:31]
	ds_read_b128 v[152:155], v207 offset:57344
	v_mfma_f32_32x32x16_bf16 v[0:15], v[156:159], v[144:147], v[0:15]
	ds_read_b128 v[144:147], v207 offset:61440
	s_waitcnt lgkmcnt(0)
	v_mfma_f32_32x32x16_bf16 v[80:95], v[140:143], v[128:131], v[80:95]
	ds_read_b128 v[140:143], v208 offset:49152
	v_mfma_f32_32x32x16_bf16 v[64:79], v[148:151], v[128:131], v[64:79]
	ds_read_b128 v[148:151], v208 offset:53248
	v_mfma_f32_32x32x16_bf16 v[16:31], v[152:155], v[128:131], v[16:31]
	ds_read_b128 v[152:155], v208 offset:57344
	v_mfma_f32_32x32x16_bf16 v[0:15], v[144:147], v[128:131], v[0:15]
	ds_read_b128 v[128:131], v208 offset:61440
	s_waitcnt lgkmcnt(0)
	v_mfma_f32_32x32x16_bf16 v[80:95], v[140:143], v[132:135], v[80:95]
	ds_read_b128 v[140:143], v209 offset:49152
	v_mfma_f32_32x32x16_bf16 v[64:79], v[148:151], v[132:135], v[64:79]
	ds_read_b128 v[144:147], v209 offset:53248
	v_mfma_f32_32x32x16_bf16 v[16:31], v[152:155], v[132:135], v[16:31]
	ds_read_b128 v[148:151], v209 offset:57344
	v_mfma_f32_32x32x16_bf16 v[0:15], v[128:131], v[132:135], v[0:15]
	ds_read_b128 v[128:131], v209 offset:61440
	s_waitcnt lgkmcnt(0)
	v_mfma_f32_32x32x16_bf16 v[80:95], v[140:143], v[136:139], v[80:95]
	ds_read_b128 v[132:135], v205
	v_mfma_f32_32x32x16_bf16 v[64:79], v[144:147], v[136:139], v[64:79]
	ds_read_b128 v[140:143], v205 offset:8192
	v_mfma_f32_32x32x16_bf16 v[16:31], v[148:151], v[136:139], v[16:31]
	ds_read_b128 v[176:179], v211
	v_mfma_f32_32x32x16_bf16 v[0:15], v[128:131], v[136:139], v[0:15]
	ds_read_b128 v[182:185], v211 offset:8192
	s_waitcnt lgkmcnt(0)
	v_mfma_f32_32x32x16_bf16 v[144:159], v[132:135], v[160:163], 0
	ds_read_b128 v[186:189], v212
	v_exp_f32_e32 v220, v112
	v_exp_f32_e32 v221, v113
	v_exp_f32_e32 v222, v114
	v_exp_f32_e32 v223, v115
	v_mfma_f32_32x32x16_bf16 v[128:143], v[140:143], v[160:163], 0
	ds_read_b128 v[216:219], v212 offset:8192
	v_exp_f32_e32 v224, v116
	v_exp_f32_e32 v225, v117
	v_exp_f32_e32 v226, v118
	v_exp_f32_e32 v227, v119
	v_mfma_f32_32x32x16_bf16 v[144:159], v[176:179], v[164:167], v[144:159]
	ds_read_b128 v[116:119], v213
	v_exp_f32_e32 v228, v120
	v_exp_f32_e32 v229, v121
	v_exp_f32_e32 v230, v122
	v_exp_f32_e32 v231, v123
	v_cvt_pk_bf16_f32 v112, v220, v221
	v_cvt_pk_bf16_f32 v113, v222, v223
	v_cvt_pk_bf16_f32 v114, v224, v225
	v_cvt_pk_bf16_f32 v115, v226, v227
	v_pk_add_f32 v[122:123], v[226:227], v[222:223]
	v_pk_add_f32 v[120:121], v[224:225], v[220:221]
	v_mfma_f32_32x32x16_bf16 v[128:143], v[182:185], v[164:167], v[128:143]
	ds_read_b128 v[176:179], v213 offset:8192
	v_exp_f32_e32 v124, v124
	v_exp_f32_e32 v125, v125
	v_exp_f32_e32 v126, v126
	v_exp_f32_e32 v127, v127
	s_waitcnt lgkmcnt(0)
	v_mfma_f32_32x32x16_bf16 v[144:159], v[186:189], v[168:171], v[144:159]
	v_add_f32_e64 v122, v230, v122
	v_add_f32_e64 v123, v231, v123
	v_add_f32_e64 v120, v228, v120
	v_add_f32_e64 v121, v229, v121
	v_exp_f32_e32 v182, v96
	v_exp_f32_e32 v183, v97
	v_exp_f32_e32 v184, v98
	v_exp_f32_e32 v185, v99
	v_cvt_pk_bf16_f32 v96, v228, v229
	v_cvt_pk_bf16_f32 v97, v230, v231
	v_cvt_pk_bf16_f32 v98, v124, v125
	v_cvt_pk_bf16_f32 v99, v126, v127
	v_pk_add_f32 v[122:123], v[126:127], v[122:123]
	v_pk_add_f32 v[120:121], v[124:125], v[120:121]
	v_mfma_f32_32x32x16_bf16 v[128:143], v[216:219], v[168:171], v[128:143]
	v_exp_f32_e32 v124, v100
	v_exp_f32_e32 v125, v101
	v_exp_f32_e32 v126, v102
	v_exp_f32_e32 v127, v103
	v_mfma_f32_32x32x16_bf16 v[144:159], v[116:119], v[172:175], v[144:159]
	v_exp_f32_e32 v186, v104
	v_exp_f32_e32 v187, v105
	v_exp_f32_e32 v188, v106
	v_exp_f32_e32 v189, v107
	v_pk_add_f32 v[106:107], v[184:185], v[122:123]
	v_pk_add_f32 v[104:105], v[182:183], v[120:121]
	v_cvt_pk_bf16_f32 v100, v182, v183
	v_cvt_pk_bf16_f32 v101, v184, v185
	v_cvt_pk_bf16_f32 v102, v124, v125
	v_cvt_pk_bf16_f32 v103, v126, v127
	v_pk_add_f32 v[118:119], v[126:127], v[106:107]
	v_pk_add_f32 v[116:117], v[124:125], v[104:105]
	v_mfma_f32_32x32x16_bf16 v[128:143], v[176:179], v[172:175], v[128:143]
	v_exp_f32_e32 v120, v108
	v_exp_f32_e32 v121, v109
	v_exp_f32_e32 v122, v110
	v_exp_f32_e32 v123, v111
	v_pk_add_f32 v[110:111], v[188:189], v[118:119]
	v_pk_add_f32 v[108:109], v[186:187], v[116:117]
	v_cvt_pk_bf16_f32 v104, v186, v187
	v_cvt_pk_bf16_f32 v105, v188, v189
	v_cvt_pk_bf16_f32 v106, v120, v121
	v_cvt_pk_bf16_f32 v107, v122, v123
	v_pk_add_f32 v[178:179], v[122:123], v[110:111]
	v_pk_add_f32 v[176:177], v[120:121], v[108:109]
	s_waitcnt vmcnt(2) lgkmcnt(0)
	s_barrier
	s_add_i32 s2, s46, 0xffff4000
	ds_read_b128 v[108:111], v236
	ds_read_b128 v[116:119], v236 offset:4096
	ds_read_b128 v[120:123], v236 offset:8192
	ds_read_b128 v[124:127], v236 offset:12288
	s_waitcnt lgkmcnt(0)
	v_mfma_f32_32x32x16_bf16 v[80:95], v[108:111], v[112:115], v[80:95]
	ds_read_b128 v[108:111], v237
	v_mfma_f32_32x32x16_bf16 v[64:79], v[116:119], v[112:115], v[64:79]
	ds_read_b128 v[116:119], v237 offset:4096
	v_mfma_f32_32x32x16_bf16 v[16:31], v[120:123], v[112:115], v[16:31]
	ds_read_b128 v[120:123], v237 offset:8192
	v_mfma_f32_32x32x16_bf16 v[0:15], v[124:127], v[112:115], v[0:15]
	ds_read_b128 v[112:115], v237 offset:12288
	s_waitcnt lgkmcnt(0)
	v_mfma_f32_32x32x16_bf16 v[80:95], v[108:111], v[96:99], v[80:95]
	ds_read_b128 v[108:111], v238
	v_mfma_f32_32x32x16_bf16 v[64:79], v[116:119], v[96:99], v[64:79]
	ds_read_b128 v[116:119], v238 offset:4096
	v_mfma_f32_32x32x16_bf16 v[16:31], v[120:123], v[96:99], v[16:31]
	ds_read_b128 v[120:123], v238 offset:8192
	v_mfma_f32_32x32x16_bf16 v[0:15], v[112:115], v[96:99], v[0:15]
	ds_read_b128 v[96:99], v238 offset:12288
	s_waitcnt lgkmcnt(0)
	v_mfma_f32_32x32x16_bf16 v[80:95], v[108:111], v[100:103], v[80:95]
	ds_read_b128 v[108:111], v239
	v_mfma_f32_32x32x16_bf16 v[64:79], v[116:119], v[100:103], v[64:79]
	ds_read_b128 v[112:115], v239 offset:4096
	v_mfma_f32_32x32x16_bf16 v[16:31], v[120:123], v[100:103], v[16:31]
	ds_read_b128 v[116:119], v239 offset:8192
	v_mfma_f32_32x32x16_bf16 v[0:15], v[96:99], v[100:103], v[0:15]
	ds_read_b128 v[120:123], v239 offset:12288
	s_waitcnt lgkmcnt(0)
	v_mfma_f32_32x32x16_bf16 v[80:95], v[108:111], v[104:107], v[80:95]
	ds_read_b128 v[96:99], v205 offset:16384
	v_mfma_f32_32x32x16_bf16 v[64:79], v[112:115], v[104:107], v[64:79]
	ds_read_b128 v[100:103], v205 offset:24576
	v_mfma_f32_32x32x16_bf16 v[16:31], v[116:119], v[104:107], v[16:31]
	ds_read_b128 v[182:185], v211 offset:16384
	v_mfma_f32_32x32x16_bf16 v[0:15], v[120:123], v[104:107], v[0:15]
	ds_read_b128 v[186:189], v211 offset:24576
	s_waitcnt lgkmcnt(0)
	v_mfma_f32_32x32x16_bf16 v[112:127], v[96:99], v[160:163], 0
	ds_read_b128 v[216:219], v212 offset:16384
	v_exp_f32_e32 v224, v144
	v_exp_f32_e32 v225, v145
	v_exp_f32_e32 v226, v146
	v_exp_f32_e32 v227, v147
	ds_read_b128 v[220:223], v212 offset:24576
	v_mfma_f32_32x32x16_bf16 v[96:111], v[100:103], v[160:163], 0
	v_exp_f32_e32 v228, v148
	v_exp_f32_e32 v229, v149
	v_exp_f32_e32 v230, v150
	v_exp_f32_e32 v231, v151
	v_mfma_f32_32x32x16_bf16 v[112:127], v[182:185], v[164:167], v[112:127]
	ds_read_b128 v[148:151], v213 offset:16384
	v_exp_f32_e32 v232, v152
	v_exp_f32_e32 v233, v153
	v_exp_f32_e32 v234, v154
	v_exp_f32_e32 v235, v155
	v_cvt_pk_bf16_f32 v144, v224, v225
	v_cvt_pk_bf16_f32 v145, v226, v227
	v_cvt_pk_bf16_f32 v146, v228, v229
	v_cvt_pk_bf16_f32 v147, v230, v231
	v_pk_add_f32 v[154:155], v[230:231], v[226:227]
	v_pk_add_f32 v[152:153], v[228:229], v[224:225]
	v_mfma_f32_32x32x16_bf16 v[96:111], v[186:189], v[164:167], v[96:111]
	ds_read_b128 v[182:185], v213 offset:24576
	v_exp_f32_e32 v156, v156
	v_exp_f32_e32 v157, v157
	v_exp_f32_e32 v158, v158
	v_exp_f32_e32 v159, v159
	s_waitcnt lgkmcnt(0)
	v_mfma_f32_32x32x16_bf16 v[112:127], v[216:219], v[168:171], v[112:127]
	v_add_f32_e64 v154, v234, v154
	v_add_f32_e64 v155, v235, v155
	v_add_f32_e64 v152, v232, v152
	v_add_f32_e64 v153, v233, v153
	v_exp_f32_e32 v186, v128
	v_exp_f32_e32 v187, v129
	v_exp_f32_e32 v188, v130
	v_exp_f32_e32 v189, v131
	v_cvt_pk_bf16_f32 v128, v232, v233
	v_cvt_pk_bf16_f32 v129, v234, v235
	v_cvt_pk_bf16_f32 v130, v156, v157
	v_cvt_pk_bf16_f32 v131, v158, v159
	v_pk_add_f32 v[154:155], v[158:159], v[154:155]
	v_pk_add_f32 v[152:153], v[156:157], v[152:153]
	v_mfma_f32_32x32x16_bf16 v[96:111], v[220:223], v[168:171], v[96:111]
	v_exp_f32_e32 v156, v132
	v_exp_f32_e32 v157, v133
	v_exp_f32_e32 v158, v134
	v_exp_f32_e32 v159, v135
	v_mfma_f32_32x32x16_bf16 v[112:127], v[148:151], v[172:175], v[112:127]
	v_exp_f32_e32 v216, v136
	v_exp_f32_e32 v217, v137
	v_exp_f32_e32 v218, v138
	v_exp_f32_e32 v219, v139
	v_pk_add_f32 v[138:139], v[188:189], v[154:155]
	v_pk_add_f32 v[136:137], v[186:187], v[152:153]
	v_cvt_pk_bf16_f32 v132, v186, v187
	v_cvt_pk_bf16_f32 v133, v188, v189
	v_cvt_pk_bf16_f32 v134, v156, v157
	v_cvt_pk_bf16_f32 v135, v158, v159
	v_pk_add_f32 v[150:151], v[158:159], v[138:139]
	v_pk_add_f32 v[148:149], v[156:157], v[136:137]
	v_mfma_f32_32x32x16_bf16 v[96:111], v[182:185], v[172:175], v[96:111]
	v_exp_f32_e32 v152, v140
	v_exp_f32_e32 v153, v141
	v_exp_f32_e32 v154, v142
	v_exp_f32_e32 v155, v143
	v_pk_add_f32 v[142:143], v[218:219], v[150:151]
	v_pk_add_f32 v[140:141], v[216:217], v[148:149]
	v_cvt_pk_bf16_f32 v136, v216, v217
	v_cvt_pk_bf16_f32 v137, v218, v219
	v_cvt_pk_bf16_f32 v138, v152, v153
	v_cvt_pk_bf16_f32 v139, v154, v155
	v_pk_add_f32 v[142:143], v[154:155], v[142:143]
	v_pk_add_f32 v[140:141], v[152:153], v[140:141]
	s_waitcnt vmcnt(0) lgkmcnt(0)
	v_add_f32_e32 v148, v176, v177
	v_add_f32_e32 v149, v178, v179
	v_add_f32_e32 v148, v148, v149
	v_add_f32_e32 v140, v140, v141
	v_add_f32_e32 v141, v142, v143
	s_barrier
	v_add_f32_e32 v148, v180, v148
	v_add_f32_e32 v140, v140, v141
	v_add_f32_e32 v180, v148, v140
	s_add_i32 s47, s47, 2
	s_addk_i32 s41, 0x80
	s_add_i32 s46, s46, 0x8000
	s_branch .LBB0_932
